# baseline (speedup 1.0000x reference)
; __device__ __forceinline__ void store8(bf16_t* dst, const float* v) { u32x4 w; w.x = pk2(v[0], v[1]); w.y = pk2(v[2], v[3]); w.z = pk2(v[4], v[5]); w.w = pk2(v[6], v[7]); *(u32x4*)dst = w; }
; __device__ __forceinline__ void store8_nt(bf16_t* dst, const float* v) { u32x4 w; w.x = pk2(v[0], v[1]); w.y = pk2(v[2], v[3]); w.z = pk2(v[4], v[5]); w.w = pk2(v[6], v[7]); __builtin_nontemporal_store(w, (u32x4*)dst); }
; __device__ __forceinline__ float sigmoidf_(float v) { return __builtin_amdgcn_rcpf(1.f + __builtin_amdgcn_exp2f(-v * LOG2E)); }
;     __device__ __forceinline__ void operator()(const pg8::f32x4 (&acc)[2][2][4][2], const pg8::Unit& u, int wr, int wc, int fr, int fq) const {
;     ...
;                         if (pn < 12) {
;                             const int t = pn >> 2, c = (pn & 3) * 256 + cl, h = c >> 7, d = c & 127;
;                             if (t == 0) {
; #pragma unroll
;                                 for (int j = 0; j < 8; ++j) v[j] *= SB_QSCALE;
;                             }
;                             bf16_t* base = t == 0 ? a.o0 : (t == 1 ? a.o1 : a.o2);
;                             store8(base + ((size_t)((bb * NH + h) * SEQ + ss)) * 128 + d, v);
;                         } else if (pn < 16) {
;                             const int t = (pn - 12) >> 1, c = ((pn - 12) & 1) * 256 + cl;
; #pragma unroll
;                             for (int j = 0; j < 8; ++j) ssq += v[j] * v[j];
;                             store8((t ? a.o4 : a.o3) + (size_t)row * 512 + c, v);
;                         } else if (pn == 16) {
;                             if (cl < 64) {
;                                 const int p = a.pos[row];
; #pragma unroll
;                                 for (int j = 0; j < 4; ++j) rope_pair(v[2 * j], v[2 * j + 1], p, (cl >> 1) + j);
;                                 store8(a.o5 + (size_t)row * 64 + cl, v);
;                             }
;                         } else {
;                             const int t = (pn - 17) >> 3, c = ((pn - 17) & 7) * 256 + cl;
; #pragma unroll
;                             for (int j = 0; j < 8; ++j) v[j] = sigmoidf_(v[j]);
;                             store8_nt((t ? a.o7 : a.o6) + (size_t)row * 2048 + c, v);
.LBB0_220:
	s_cmp_gt_i32 s14, 11
	s_cselect_b64 s[54:55], -1, 0
	s_cmp_gt_u32 s14, 15
	s_cselect_b64 s[58:59], -1, 0
	s_cmp_lg_u32 s14, 16
	s_cselect_b64 s[52:53], -1, 0
	s_sub_i32 s9, s14, 17
	s_lshl_b32 s10, s9, 8
	s_and_b32 s41, s10, 0x700
	s_cmp_lt_u32 s9, 8
	s_cselect_b64 s[50:51], -1, 0
	s_lshl_b32 s9, s14, 8
	s_and_b32 s39, s9, 0x100
	s_and_b32 s9, s14, 14
	s_cmp_eq_u32 s9, 12
	s_cselect_b64 s[48:49], -1, 0
	s_cmp_gt_u32 s14, 3
	s_cselect_b64 s[10:11], -1, 0
	s_and_b32 s15, s14, -4
	s_cmp_eq_u32 s15, 4
	s_cselect_b64 s[46:47], -1, 0
	s_lshl_b32 s8, s8, 8
	s_add_i32 s56, s8, s94
	v_or_b32_e32 v152, s56, v138
	v_ashrrev_i32_e32 v153, 31, v152
	v_lshlrev_b64 v[156:157], 12, v[152:153]
	v_lshlrev_b64 v[154:155], 10, v[152:153]
	s_mov_b64 s[8:9], -1
	s_and_b64 vcc, exec, s[54:55]
	s_cbranch_vccz .LBB0_231
	s_and_b64 vcc, exec, s[58:59]
	s_cbranch_vccz .LBB0_228
	s_and_b64 vcc, exec, s[52:53]
	s_cbranch_vccz .LBB0_224
	s_and_b64 s[8:9], s[50:51], exec
	v_or_b32_e32 v136, s41, v140
	s_cselect_b32 s9, s17, s91
	s_cselect_b32 s8, s16, s90
	v_lshl_add_u64 v[174:175], s[8:9], 0, v[156:157]
	v_lshlrev_b32_e32 v136, 1, v136
	v_lshl_add_u64 v[182:183], v[174:175], 0, v[136:137]
	v_cvt_pk_bf16_f32 v174, v124, v125
	v_cvt_pk_bf16_f32 v175, v126, v127
	v_cvt_pk_bf16_f32 v176, v120, v121
	v_cvt_pk_bf16_f32 v177, v122, v123
	global_store_dwordx4 v[182:183], v[174:177], off nt
	s_mov_b64 s[8:9], 0

; __device__ __forceinline__ void store8(bf16_t* dst, const float* v) { u32x4 w; w.x = pk2(v[0], v[1]); w.y = pk2(v[2], v[3]); w.z = pk2(v[4], v[5]); w.w = pk2(v[6], v[7]); *(u32x4*)dst = w; }
; __device__ __forceinline__ void store8_nt(bf16_t* dst, const float* v) { u32x4 w; w.x = pk2(v[0], v[1]); w.y = pk2(v[2], v[3]); w.z = pk2(v[4], v[5]); w.w = pk2(v[6], v[7]); __builtin_nontemporal_store(w, (u32x4*)dst); }
; __device__ __forceinline__ float sigmoidf_(float v) { return __builtin_amdgcn_rcpf(1.f + __builtin_amdgcn_exp2f(-v * LOG2E)); }
;     __device__ __forceinline__ void operator()(const pg8::f32x4 (&acc)[2][2][4][2], const pg8::Unit& u, int wr, int wc, int fr, int fq) const {
;     ...
;                         if (pn < 12) {
;                             const int t = pn >> 2, c = (pn & 3) * 256 + cl, h = c >> 7, d = c & 127;
;                             if (t == 0) {
; #pragma unroll
;                                 for (int j = 0; j < 8; ++j) v[j] *= SB_QSCALE;
;                             }
;                             bf16_t* base = t == 0 ? a.o0 : (t == 1 ? a.o1 : a.o2);
;                             store8(base + ((size_t)((bb * NH + h) * SEQ + ss)) * 128 + d, v);
;                         } else if (pn < 16) {
;                             const int t = (pn - 12) >> 1, c = ((pn - 12) & 1) * 256 + cl;
; #pragma unroll
;                             for (int j = 0; j < 8; ++j) ssq += v[j] * v[j];
;                             store8((t ? a.o4 : a.o3) + (size_t)row * 512 + c, v);
;                         } else if (pn == 16) {
;                             if (cl < 64) {
;                                 const int p = a.pos[row];
; #pragma unroll
;                                 for (int j = 0; j < 4; ++j) rope_pair(v[2 * j], v[2 * j + 1], p, (cl >> 1) + j);
;                                 store8(a.o5 + (size_t)row * 64 + cl, v);
;                             }
;                         } else {
;                             const int t = (pn - 17) >> 3, c = ((pn - 17) & 7) * 256 + cl;
; #pragma unroll
;                             for (int j = 0; j < 8; ++j) v[j] = sigmoidf_(v[j]);
;                             store8_nt((t ? a.o7 : a.o6) + (size_t)row * 2048 + c, v);
.LBB0_237:
	v_cndmask_b32_e64 v120, 0, 1, s[54:55]
	v_cmp_ne_u32_e64 s[12:13], 1, v120
	v_cndmask_b32_e64 v120, 0, 1, s[58:59]
	s_mov_b64 s[60:61], -1
	s_andn2_b64 vcc, exec, s[54:55]
	v_cmp_ne_u32_e64 s[8:9], 1, v120
	s_cbranch_vccnz .LBB0_245
	s_and_b64 vcc, exec, s[8:9]
	s_mov_b64 s[54:55], -1
	s_cbranch_vccnz .LBB0_242
	s_andn2_b64 vcc, exec, s[52:53]
	s_cbranch_vccnz .LBB0_241
	s_and_b64 s[54:55], s[50:51], exec
	s_cselect_b32 s55, s17, s91
	s_cselect_b32 s54, s16, s90
	v_lshl_add_u64 v[120:121], s[54:55], 0, v[156:157]
	v_add_lshl_u32 v136, s41, v140, 1
	v_lshl_add_u64 v[124:125], v[120:121], 0, v[136:137]
	v_cvt_pk_bf16_f32 v120, v116, v117
	v_cvt_pk_bf16_f32 v121, v118, v119
	v_cvt_pk_bf16_f32 v122, v112, v113
	v_cvt_pk_bf16_f32 v123, v114, v115
	global_store_dwordx4 v[124:125], v[120:123], off offset:256 nt

; __device__ __forceinline__ void store8_nt(bf16_t* dst, const float* v) { u32x4 w; w.x = pk2(v[0], v[1]); w.y = pk2(v[2], v[3]); w.z = pk2(v[4], v[5]); w.w = pk2(v[6], v[7]); __builtin_nontemporal_store(w, (u32x4*)dst); }
; __device__ __forceinline__ float sigmoidf_(float v) { return __builtin_amdgcn_rcpf(1.f + __builtin_amdgcn_exp2f(-v * LOG2E)); }
;     __device__ __forceinline__ void operator()(const pg8::f32x4 (&acc)[2][2][4][2], const pg8::Unit& u, int wr, int wc, int fr, int fq) const {
;     ...
;                         } else {
;                             const int t = (pn - 17) >> 3, c = ((pn - 17) & 7) * 256 + cl;
; #pragma unroll
;                             for (int j = 0; j < 8; ++j) v[j] = sigmoidf_(v[j]);
;                             store8_nt((t ? a.o7 : a.o6) + (size_t)row * 2048 + c, v);
.LBB0_260:
	s_and_b64 vcc, exec, s[8:9]
	s_cbranch_vccnz .LBB0_267
	s_andn2_b64 vcc, exec, s[52:53]
	s_cbranch_vccnz .LBB0_263
	s_and_b64 s[14:15], s[50:51], exec
	v_or_b32_e32 v122, s41, v140
	s_cselect_b32 s15, s17, s91
	s_cselect_b32 s14, s16, s90
	v_lshl_add_u64 v[118:119], s[14:15], 0, v[114:115]
	v_lshlrev_b32_e32 v136, 1, v122
	v_lshl_add_u64 v[122:123], v[118:119], 0, v[136:137]
	v_cvt_pk_bf16_f32 v118, v108, v109
	v_cvt_pk_bf16_f32 v119, v110, v111
	v_cvt_pk_bf16_f32 v120, v104, v105
	v_cvt_pk_bf16_f32 v121, v106, v107
	s_mov_b64 s[14:15], 0
	global_store_dwordx4 v[122:123], v[118:121], off nt

; __device__ __forceinline__ void store8_nt(bf16_t* dst, const float* v) { u32x4 w; w.x = pk2(v[0], v[1]); w.y = pk2(v[2], v[3]); w.z = pk2(v[4], v[5]); w.w = pk2(v[6], v[7]); __builtin_nontemporal_store(w, (u32x4*)dst); }
; __device__ __forceinline__ float sigmoidf_(float v) { return __builtin_amdgcn_rcpf(1.f + __builtin_amdgcn_exp2f(-v * LOG2E)); }
;     __device__ __forceinline__ void operator()(const pg8::f32x4 (&acc)[2][2][4][2], const pg8::Unit& u, int wr, int wc, int fr, int fq) const {
;     ...
;                         } else {
;                             const int t = (pn - 17) >> 3, c = ((pn - 17) & 7) * 256 + cl;
; #pragma unroll
;                             for (int j = 0; j < 8; ++j) v[j] = sigmoidf_(v[j]);
;                             store8_nt((t ? a.o7 : a.o6) + (size_t)row * 2048 + c, v);
.LBB0_275:
	s_and_b64 vcc, exec, s[8:9]
	s_cbranch_vccnz .LBB0_279
	s_andn2_b64 vcc, exec, s[52:53]
	s_cbranch_vccnz .LBB0_278
	s_and_b64 s[14:15], s[50:51], exec
	s_cselect_b32 s15, s17, s91
	s_cselect_b32 s14, s16, s90
	v_lshl_add_u64 v[104:105], s[14:15], 0, v[114:115]
	v_add_lshl_u32 v136, s41, v140, 1
	v_lshl_add_u64 v[108:109], v[104:105], 0, v[136:137]
	v_cvt_pk_bf16_f32 v104, v100, v101
	v_cvt_pk_bf16_f32 v105, v102, v103
	v_cvt_pk_bf16_f32 v106, v96, v97
	v_cvt_pk_bf16_f32 v107, v98, v99
	global_store_dwordx4 v[108:109], v[104:107], off offset:256 nt

; __device__ __forceinline__ void store8_nt(bf16_t* dst, const float* v) { u32x4 w; w.x = pk2(v[0], v[1]); w.y = pk2(v[2], v[3]); w.z = pk2(v[4], v[5]); w.w = pk2(v[6], v[7]); __builtin_nontemporal_store(w, (u32x4*)dst); }
; __device__ __forceinline__ float sigmoidf_(float v) { return __builtin_amdgcn_rcpf(1.f + __builtin_amdgcn_exp2f(-v * LOG2E)); }
;     __device__ __forceinline__ void operator()(const pg8::f32x4 (&acc)[2][2][4][2], const pg8::Unit& u, int wr, int wc, int fr, int fq) const {
;     ...
;                         } else {
;                             const int t = (pn - 17) >> 3, c = ((pn - 17) & 7) * 256 + cl;
; #pragma unroll
;                             for (int j = 0; j < 8; ++j) v[j] = sigmoidf_(v[j]);
;                             store8_nt((t ? a.o7 : a.o6) + (size_t)row * 2048 + c, v);
.LBB0_295:
	s_and_b64 vcc, exec, s[8:9]
	s_cbranch_vccnz .LBB0_302
	s_andn2_b64 vcc, exec, s[52:53]
	s_cbranch_vccnz .LBB0_298
	s_and_b64 s[58:59], s[50:51], exec
	v_or_b32_e32 v106, s41, v140
	s_cselect_b32 s59, s17, s91
	s_cselect_b32 s58, s16, s90
	v_lshl_add_u64 v[102:103], s[58:59], 0, v[98:99]
	v_lshlrev_b32_e32 v136, 1, v106
	v_lshl_add_u64 v[106:107], v[102:103], 0, v[136:137]
	v_cvt_pk_bf16_f32 v102, v92, v93
	v_cvt_pk_bf16_f32 v103, v94, v95
	v_cvt_pk_bf16_f32 v104, v88, v89
	v_cvt_pk_bf16_f32 v105, v90, v91
	s_mov_b64 s[58:59], 0
	global_store_dwordx4 v[106:107], v[102:105], off nt

; __device__ __forceinline__ void store8_nt(bf16_t* dst, const float* v) { u32x4 w; w.x = pk2(v[0], v[1]); w.y = pk2(v[2], v[3]); w.z = pk2(v[4], v[5]); w.w = pk2(v[6], v[7]); __builtin_nontemporal_store(w, (u32x4*)dst); }
; __device__ __forceinline__ float sigmoidf_(float v) { return __builtin_amdgcn_rcpf(1.f + __builtin_amdgcn_exp2f(-v * LOG2E)); }
;     __device__ __forceinline__ void operator()(const pg8::f32x4 (&acc)[2][2][4][2], const pg8::Unit& u, int wr, int wc, int fr, int fq) const {
;     ...
;                         } else {
;                             const int t = (pn - 17) >> 3, c = ((pn - 17) & 7) * 256 + cl;
; #pragma unroll
;                             for (int j = 0; j < 8; ++j) v[j] = sigmoidf_(v[j]);
;                             store8_nt((t ? a.o7 : a.o6) + (size_t)row * 2048 + c, v);
.LBB0_310:
	s_and_b64 vcc, exec, s[8:9]
	s_cbranch_vccnz .LBB0_314
	s_andn2_b64 vcc, exec, s[52:53]
	s_cbranch_vccnz .LBB0_313
	s_and_b64 s[58:59], s[50:51], exec
	s_cselect_b32 s59, s17, s91
	s_cselect_b32 s58, s16, s90
	v_lshl_add_u64 v[88:89], s[58:59], 0, v[98:99]
	v_add_lshl_u32 v136, s41, v140, 1
	v_lshl_add_u64 v[92:93], v[88:89], 0, v[136:137]
	v_cvt_pk_bf16_f32 v88, v84, v85
	v_cvt_pk_bf16_f32 v89, v86, v87
	v_cvt_pk_bf16_f32 v90, v80, v81
	v_cvt_pk_bf16_f32 v91, v82, v83
	global_store_dwordx4 v[92:93], v[88:91], off offset:256 nt

; __device__ __forceinline__ void store8_nt(bf16_t* dst, const float* v) { u32x4 w; w.x = pk2(v[0], v[1]); w.y = pk2(v[2], v[3]); w.z = pk2(v[4], v[5]); w.w = pk2(v[6], v[7]); __builtin_nontemporal_store(w, (u32x4*)dst); }
; __device__ __forceinline__ float sigmoidf_(float v) { return __builtin_amdgcn_rcpf(1.f + __builtin_amdgcn_exp2f(-v * LOG2E)); }
;     __device__ __forceinline__ void operator()(const pg8::f32x4 (&acc)[2][2][4][2], const pg8::Unit& u, int wr, int wc, int fr, int fq) const {
;     ...
;                         } else {
;                             const int t = (pn - 17) >> 3, c = ((pn - 17) & 7) * 256 + cl;
; #pragma unroll
;                             for (int j = 0; j < 8; ++j) v[j] = sigmoidf_(v[j]);
;                             store8_nt((t ? a.o7 : a.o6) + (size_t)row * 2048 + c, v);
.LBB0_330:
	s_and_b64 vcc, exec, s[8:9]
	s_cbranch_vccnz .LBB0_337
	s_andn2_b64 vcc, exec, s[52:53]
	s_cbranch_vccnz .LBB0_333
	s_and_b64 s[58:59], s[50:51], exec
	v_or_b32_e32 v90, s41, v140
	s_cselect_b32 s59, s17, s91
	s_cselect_b32 s58, s16, s90
	v_lshl_add_u64 v[86:87], s[58:59], 0, v[82:83]
	v_lshlrev_b32_e32 v136, 1, v90
	v_lshl_add_u64 v[90:91], v[86:87], 0, v[136:137]
	v_cvt_pk_bf16_f32 v86, v76, v77
	v_cvt_pk_bf16_f32 v87, v78, v79
	v_cvt_pk_bf16_f32 v88, v72, v73
	v_cvt_pk_bf16_f32 v89, v74, v75
	s_mov_b64 s[58:59], 0
	global_store_dwordx4 v[90:91], v[86:89], off nt

; __device__ __forceinline__ void store8_nt(bf16_t* dst, const float* v) { u32x4 w; w.x = pk2(v[0], v[1]); w.y = pk2(v[2], v[3]); w.z = pk2(v[4], v[5]); w.w = pk2(v[6], v[7]); __builtin_nontemporal_store(w, (u32x4*)dst); }
; __device__ __forceinline__ float sigmoidf_(float v) { return __builtin_amdgcn_rcpf(1.f + __builtin_amdgcn_exp2f(-v * LOG2E)); }
;     __device__ __forceinline__ void operator()(const pg8::f32x4 (&acc)[2][2][4][2], const pg8::Unit& u, int wr, int wc, int fr, int fq) const {
;     ...
;                         } else {
;                             const int t = (pn - 17) >> 3, c = ((pn - 17) & 7) * 256 + cl;
; #pragma unroll
;                             for (int j = 0; j < 8; ++j) v[j] = sigmoidf_(v[j]);
;                             store8_nt((t ? a.o7 : a.o6) + (size_t)row * 2048 + c, v);
.LBB0_345:
	s_and_b64 vcc, exec, s[8:9]
	s_cbranch_vccnz .LBB0_349
	s_andn2_b64 vcc, exec, s[52:53]
	s_cbranch_vccnz .LBB0_348
	s_and_b64 s[58:59], s[50:51], exec
	s_cselect_b32 s59, s17, s91
	s_cselect_b32 s58, s16, s90
	v_lshl_add_u64 v[72:73], s[58:59], 0, v[82:83]
	v_add_lshl_u32 v136, s41, v140, 1
	v_lshl_add_u64 v[76:77], v[72:73], 0, v[136:137]
	v_cvt_pk_bf16_f32 v72, v68, v69
	v_cvt_pk_bf16_f32 v73, v70, v71
	v_cvt_pk_bf16_f32 v74, v64, v65
	v_cvt_pk_bf16_f32 v75, v66, v67
	global_store_dwordx4 v[76:77], v[72:75], off offset:256 nt

; __device__ __forceinline__ void store8_nt(bf16_t* dst, const float* v) { u32x4 w; w.x = pk2(v[0], v[1]); w.y = pk2(v[2], v[3]); w.z = pk2(v[4], v[5]); w.w = pk2(v[6], v[7]); __builtin_nontemporal_store(w, (u32x4*)dst); }
; __device__ __forceinline__ float sigmoidf_(float v) { return __builtin_amdgcn_rcpf(1.f + __builtin_amdgcn_exp2f(-v * LOG2E)); }
;     __device__ __forceinline__ void operator()(const pg8::f32x4 (&acc)[2][2][4][2], const pg8::Unit& u, int wr, int wc, int fr, int fq) const {
;     ...
;                 const int row = u.pm * 256 + ai * 128 + wr * 64 + m * 16 + fr;
;                 const int bb = row >> 13, ss = row & 8191;
;     ...
;                         } else {
;                             const int t = (pn - 17) >> 3, c = ((pn - 17) & 7) * 256 + cl;
; #pragma unroll
;                             for (int j = 0; j < 8; ++j) v[j] = sigmoidf_(v[j]);
;                             store8_nt((t ? a.o7 : a.o6) + (size_t)row * 2048 + c, v);
.LBB0_360:
	s_addk_i32 s56, 0x80
	v_or_b32_e32 v64, s56, v138
	s_waitcnt lgkmcnt(0)
	v_ashrrev_i32_e32 v65, 31, v64
	v_lshlrev_b64 v[68:69], 12, v[64:65]
	v_lshlrev_b64 v[66:67], 10, v[64:65]
	s_and_b64 vcc, exec, s[12:13]
	s_mov_b64 s[58:59], -1
	s_cbranch_vccnz .LBB0_371
	s_and_b64 vcc, exec, s[8:9]
	s_cbranch_vccnz .LBB0_368
	s_andn2_b64 vcc, exec, s[52:53]
	s_cbranch_vccnz .LBB0_364
	s_and_b64 s[58:59], s[50:51], exec
	v_or_b32_e32 v74, s41, v140
	s_cselect_b32 s59, s17, s91
	s_cselect_b32 s58, s16, s90
	v_lshl_add_u64 v[70:71], s[58:59], 0, v[68:69]
	v_lshlrev_b32_e32 v136, 1, v74
	v_lshl_add_u64 v[74:75], v[70:71], 0, v[136:137]
	v_cvt_pk_bf16_f32 v70, v60, v61
	v_cvt_pk_bf16_f32 v71, v62, v63
	v_cvt_pk_bf16_f32 v72, v56, v57
	v_cvt_pk_bf16_f32 v73, v58, v59
	s_mov_b64 s[58:59], 0
	global_store_dwordx4 v[74:75], v[70:73], off nt

; __device__ __forceinline__ void store8_nt(bf16_t* dst, const float* v) { u32x4 w; w.x = pk2(v[0], v[1]); w.y = pk2(v[2], v[3]); w.z = pk2(v[4], v[5]); w.w = pk2(v[6], v[7]); __builtin_nontemporal_store(w, (u32x4*)dst); }
; __device__ __forceinline__ float sigmoidf_(float v) { return __builtin_amdgcn_rcpf(1.f + __builtin_amdgcn_exp2f(-v * LOG2E)); }
;     __device__ __forceinline__ void operator()(const pg8::f32x4 (&acc)[2][2][4][2], const pg8::Unit& u, int wr, int wc, int fr, int fq) const {
;     ...
;                         } else {
;                             const int t = (pn - 17) >> 3, c = ((pn - 17) & 7) * 256 + cl;
; #pragma unroll
;                             for (int j = 0; j < 8; ++j) v[j] = sigmoidf_(v[j]);
;                             store8_nt((t ? a.o7 : a.o6) + (size_t)row * 2048 + c, v);
.LBB0_380:
	s_and_b64 vcc, exec, s[8:9]
	s_cbranch_vccnz .LBB0_384
	s_andn2_b64 vcc, exec, s[52:53]
	s_cbranch_vccnz .LBB0_383
	s_and_b64 s[58:59], s[50:51], exec
	s_cselect_b32 s59, s17, s91
	s_cselect_b32 s58, s16, s90
	v_lshl_add_u64 v[56:57], s[58:59], 0, v[68:69]
	v_add_lshl_u32 v136, s41, v140, 1
	v_lshl_add_u64 v[60:61], v[56:57], 0, v[136:137]
	v_cvt_pk_bf16_f32 v56, v52, v53
	v_cvt_pk_bf16_f32 v57, v54, v55
	v_cvt_pk_bf16_f32 v58, v48, v49
	v_cvt_pk_bf16_f32 v59, v50, v51
	global_store_dwordx4 v[60:61], v[56:59], off offset:256 nt

; __device__ __forceinline__ void store8_nt(bf16_t* dst, const float* v) { u32x4 w; w.x = pk2(v[0], v[1]); w.y = pk2(v[2], v[3]); w.z = pk2(v[4], v[5]); w.w = pk2(v[6], v[7]); __builtin_nontemporal_store(w, (u32x4*)dst); }
; __device__ __forceinline__ float sigmoidf_(float v) { return __builtin_amdgcn_rcpf(1.f + __builtin_amdgcn_exp2f(-v * LOG2E)); }
;     __device__ __forceinline__ void operator()(const pg8::f32x4 (&acc)[2][2][4][2], const pg8::Unit& u, int wr, int wc, int fr, int fq) const {
;     ...
;                         } else {
;                             const int t = (pn - 17) >> 3, c = ((pn - 17) & 7) * 256 + cl;
; #pragma unroll
;                             for (int j = 0; j < 8; ++j) v[j] = sigmoidf_(v[j]);
;                             store8_nt((t ? a.o7 : a.o6) + (size_t)row * 2048 + c, v);
.LBB0_400:
	s_and_b64 vcc, exec, s[8:9]
	s_cbranch_vccnz .LBB0_407
	s_andn2_b64 vcc, exec, s[52:53]
	s_cbranch_vccnz .LBB0_403
	s_and_b64 s[58:59], s[50:51], exec
	v_or_b32_e32 v58, s41, v140
	s_cselect_b32 s59, s17, s91
	s_cselect_b32 s58, s16, s90
	v_lshl_add_u64 v[54:55], s[58:59], 0, v[50:51]
	v_lshlrev_b32_e32 v136, 1, v58
	v_lshl_add_u64 v[58:59], v[54:55], 0, v[136:137]
	v_cvt_pk_bf16_f32 v54, v44, v45
	v_cvt_pk_bf16_f32 v55, v46, v47
	v_cvt_pk_bf16_f32 v56, v40, v41
	v_cvt_pk_bf16_f32 v57, v42, v43
	s_mov_b64 s[58:59], 0
	global_store_dwordx4 v[58:59], v[54:57], off nt

; __device__ __forceinline__ void store8_nt(bf16_t* dst, const float* v) { u32x4 w; w.x = pk2(v[0], v[1]); w.y = pk2(v[2], v[3]); w.z = pk2(v[4], v[5]); w.w = pk2(v[6], v[7]); __builtin_nontemporal_store(w, (u32x4*)dst); }
; __device__ __forceinline__ float sigmoidf_(float v) { return __builtin_amdgcn_rcpf(1.f + __builtin_amdgcn_exp2f(-v * LOG2E)); }
;     __device__ __forceinline__ void operator()(const pg8::f32x4 (&acc)[2][2][4][2], const pg8::Unit& u, int wr, int wc, int fr, int fq) const {
;     ...
;                         } else {
;                             const int t = (pn - 17) >> 3, c = ((pn - 17) & 7) * 256 + cl;
; #pragma unroll
;                             for (int j = 0; j < 8; ++j) v[j] = sigmoidf_(v[j]);
;                             store8_nt((t ? a.o7 : a.o6) + (size_t)row * 2048 + c, v);
.LBB0_415:
	s_and_b64 vcc, exec, s[8:9]
	s_cbranch_vccnz .LBB0_419
	s_andn2_b64 vcc, exec, s[52:53]
	s_cbranch_vccnz .LBB0_418
	s_and_b64 s[58:59], s[50:51], exec
	s_cselect_b32 s59, s17, s91
	s_cselect_b32 s58, s16, s90
	v_lshl_add_u64 v[40:41], s[58:59], 0, v[50:51]
	v_add_lshl_u32 v136, s41, v140, 1
	v_lshl_add_u64 v[44:45], v[40:41], 0, v[136:137]
	v_cvt_pk_bf16_f32 v40, v36, v37
	v_cvt_pk_bf16_f32 v41, v38, v39
	v_cvt_pk_bf16_f32 v42, v32, v33
	v_cvt_pk_bf16_f32 v43, v34, v35
	global_store_dwordx4 v[44:45], v[40:43], off offset:256 nt

; __device__ __forceinline__ void store8_nt(bf16_t* dst, const float* v) { u32x4 w; w.x = pk2(v[0], v[1]); w.y = pk2(v[2], v[3]); w.z = pk2(v[4], v[5]); w.w = pk2(v[6], v[7]); __builtin_nontemporal_store(w, (u32x4*)dst); }
; __device__ __forceinline__ float sigmoidf_(float v) { return __builtin_amdgcn_rcpf(1.f + __builtin_amdgcn_exp2f(-v * LOG2E)); }
;     __device__ __forceinline__ void operator()(const pg8::f32x4 (&acc)[2][2][4][2], const pg8::Unit& u, int wr, int wc, int fr, int fq) const {
;     ...
;                         } else {
;                             const int t = (pn - 17) >> 3, c = ((pn - 17) & 7) * 256 + cl;
; #pragma unroll
;                             for (int j = 0; j < 8; ++j) v[j] = sigmoidf_(v[j]);
;                             store8_nt((t ? a.o7 : a.o6) + (size_t)row * 2048 + c, v);
.LBB0_435:
	s_and_b64 vcc, exec, s[8:9]
	s_cbranch_vccnz .LBB0_442
	s_andn2_b64 vcc, exec, s[52:53]
	s_cbranch_vccnz .LBB0_438
	s_and_b64 s[58:59], s[50:51], exec
	v_or_b32_e32 v42, s41, v140
	s_cselect_b32 s59, s17, s91
	s_cselect_b32 s58, s16, s90
	v_lshl_add_u64 v[38:39], s[58:59], 0, v[34:35]
	v_lshlrev_b32_e32 v136, 1, v42
	v_lshl_add_u64 v[42:43], v[38:39], 0, v[136:137]
	v_cvt_pk_bf16_f32 v38, v28, v29
	v_cvt_pk_bf16_f32 v39, v30, v31
	v_cvt_pk_bf16_f32 v40, v24, v25
	v_cvt_pk_bf16_f32 v41, v26, v27
	s_mov_b64 s[58:59], 0
	global_store_dwordx4 v[42:43], v[38:41], off nt

; __device__ __forceinline__ void store8_nt(bf16_t* dst, const float* v) { u32x4 w; w.x = pk2(v[0], v[1]); w.y = pk2(v[2], v[3]); w.z = pk2(v[4], v[5]); w.w = pk2(v[6], v[7]); __builtin_nontemporal_store(w, (u32x4*)dst); }
; __device__ __forceinline__ float sigmoidf_(float v) { return __builtin_amdgcn_rcpf(1.f + __builtin_amdgcn_exp2f(-v * LOG2E)); }
;     __device__ __forceinline__ void operator()(const pg8::f32x4 (&acc)[2][2][4][2], const pg8::Unit& u, int wr, int wc, int fr, int fq) const {
;     ...
;                         } else {
;                             const int t = (pn - 17) >> 3, c = ((pn - 17) & 7) * 256 + cl;
; #pragma unroll
;                             for (int j = 0; j < 8; ++j) v[j] = sigmoidf_(v[j]);
;                             store8_nt((t ? a.o7 : a.o6) + (size_t)row * 2048 + c, v);
.LBB0_450:
	s_and_b64 vcc, exec, s[8:9]
	s_cbranch_vccnz .LBB0_454
	s_andn2_b64 vcc, exec, s[52:53]
	s_cbranch_vccnz .LBB0_453
	s_and_b64 s[58:59], s[50:51], exec
	s_cselect_b32 s59, s17, s91
	s_cselect_b32 s58, s16, s90
	v_lshl_add_u64 v[24:25], s[58:59], 0, v[34:35]
	v_add_lshl_u32 v136, s41, v140, 1
	v_lshl_add_u64 v[28:29], v[24:25], 0, v[136:137]
	v_cvt_pk_bf16_f32 v24, v20, v21
	v_cvt_pk_bf16_f32 v25, v22, v23
	v_cvt_pk_bf16_f32 v26, v16, v17
	v_cvt_pk_bf16_f32 v27, v18, v19
	global_store_dwordx4 v[28:29], v[24:27], off offset:256 nt

; __device__ __forceinline__ void store8_nt(bf16_t* dst, const float* v) { u32x4 w; w.x = pk2(v[0], v[1]); w.y = pk2(v[2], v[3]); w.z = pk2(v[4], v[5]); w.w = pk2(v[6], v[7]); __builtin_nontemporal_store(w, (u32x4*)dst); }
; __device__ __forceinline__ float sigmoidf_(float v) { return __builtin_amdgcn_rcpf(1.f + __builtin_amdgcn_exp2f(-v * LOG2E)); }
;     __device__ __forceinline__ void operator()(const pg8::f32x4 (&acc)[2][2][4][2], const pg8::Unit& u, int wr, int wc, int fr, int fq) const {
;     ...
;                         } else {
;                             const int t = (pn - 17) >> 3, c = ((pn - 17) & 7) * 256 + cl;
; #pragma unroll
;                             for (int j = 0; j < 8; ++j) v[j] = sigmoidf_(v[j]);
;                             store8_nt((t ? a.o7 : a.o6) + (size_t)row * 2048 + c, v);
.LBB0_471:
	s_and_b64 vcc, exec, s[8:9]
	s_cbranch_vccnz .LBB0_478
	s_andn2_b64 vcc, exec, s[52:53]
	s_cbranch_vccnz .LBB0_474
	s_and_b64 s[58:59], s[50:51], exec
	v_or_b32_e32 v26, s41, v140
	s_cselect_b32 s59, s17, s91
	s_cselect_b32 s58, s16, s90
	v_lshl_add_u64 v[22:23], s[58:59], 0, v[18:19]
	v_lshlrev_b32_e32 v136, 1, v26
	v_lshl_add_u64 v[26:27], v[22:23], 0, v[136:137]
	v_cvt_pk_bf16_f32 v22, v12, v13
	v_cvt_pk_bf16_f32 v23, v14, v15
	v_cvt_pk_bf16_f32 v24, v8, v9
	v_cvt_pk_bf16_f32 v25, v10, v11
	s_mov_b64 s[58:59], 0
	global_store_dwordx4 v[26:27], v[22:25], off nt

; __device__ __forceinline__ void store8_nt(bf16_t* dst, const float* v) { u32x4 w; w.x = pk2(v[0], v[1]); w.y = pk2(v[2], v[3]); w.z = pk2(v[4], v[5]); w.w = pk2(v[6], v[7]); __builtin_nontemporal_store(w, (u32x4*)dst); }
; __device__ __forceinline__ float sigmoidf_(float v) { return __builtin_amdgcn_rcpf(1.f + __builtin_amdgcn_exp2f(-v * LOG2E)); }
;     __device__ __forceinline__ void operator()(const pg8::f32x4 (&acc)[2][2][4][2], const pg8::Unit& u, int wr, int wc, int fr, int fq) const {
;     ...
;                         } else {
;                             const int t = (pn - 17) >> 3, c = ((pn - 17) & 7) * 256 + cl;
; #pragma unroll
;                             for (int j = 0; j < 8; ++j) v[j] = sigmoidf_(v[j]);
;                             store8_nt((t ? a.o7 : a.o6) + (size_t)row * 2048 + c, v);
.LBB0_486:
	s_and_b64 vcc, exec, s[8:9]
	s_mov_b64 s[8:9], -1
	s_cbranch_vccnz .LBB0_490
	s_andn2_b64 vcc, exec, s[52:53]
	s_cbranch_vccnz .LBB0_489
	s_and_b64 s[8:9], s[50:51], exec
	s_cselect_b32 s9, s17, s91
	s_cselect_b32 s8, s16, s90
	v_lshl_add_u64 v[8:9], s[8:9], 0, v[18:19]
	v_add_lshl_u32 v136, s41, v140, 1
	v_lshl_add_u64 v[12:13], v[8:9], 0, v[136:137]
	v_cvt_pk_bf16_f32 v8, v4, v5
	v_cvt_pk_bf16_f32 v9, v6, v7
	v_cvt_pk_bf16_f32 v10, v0, v1
	v_cvt_pk_bf16_f32 v11, v2, v3
	global_store_dwordx4 v[12:13], v[8:11], off offset:256 nt

; __device__ __forceinline__ void store8(bf16_t* dst, const float* v) { u32x4 w; w.x = pk2(v[0], v[1]); w.y = pk2(v[2], v[3]); w.z = pk2(v[4], v[5]); w.w = pk2(v[6], v[7]); *(u32x4*)dst = w; }
; __device__ __forceinline__ void load8(const bf16_t* src, float* v) { const u32x4 w = *(const u32x4*)src; v[0] = bf_lo(w.x); v[1] = bf_hi(w.x); v[2] = bf_lo(w.y); v[3] = bf_hi(w.y); v[4] = bf_lo(w.z); v[5] = bf_hi(w.z); v[6] = bf_lo(w.w); v[7] = bf_hi(w.w); }
; __device__ __forceinline__ float sigmoidf_(float v) { return __builtin_amdgcn_rcpf(1.f + __builtin_amdgcn_exp2f(-v * LOG2E)); }
;     __device__ __forceinline__ void operator()(const pg8::f32x4 (&acc)[2][2][4][2], const pg8::Unit& u, int wr, int wc, int fr, int fq) const {
;     ...
;                     } else if constexpr (KIND == EK_MIX1) {
;                         const size_t off = (size_t)row * 2048 + pn * 256 + cl; float g[8]; load8(a.g0 + off, g);
; #pragma unroll
;                         for (int j = 0; j < 8; ++j) v[j] *= g[j];
;                         store8(a.o0 + off, v);
.LBB0_1052:
	v_lshl_add_u32 v148, s26, 8, v137
	s_lshl_b32 s26, s27, 9
	v_lshlrev_b32_e32 v148, 12, v148
	v_lshl_add_u32 v149, v136, 1, s26
	v_add_u32_e32 v148, v148, v149
	global_load_dwordx4 v[154:157], v148, s[8:9]
	global_load_dwordx4 v[158:161], v148, s[8:9] offset:256
	v_add_u32_e32 v149, 0x10000, v148
	global_load_dwordx4 v[162:165], v149, s[8:9]
	global_load_dwordx4 v[168:171], v149, s[8:9] offset:256
	v_add_u32_e32 v149, 0x20000, v148
	global_load_dwordx4 v[182:185], v149, s[8:9]
	global_load_dwordx4 v[186:189], v149, s[8:9] offset:256
	v_add_u32_e32 v149, 0x30000, v148
	global_load_dwordx4 v[190:193], v149, s[8:9]
	global_load_dwordx4 v[194:197], v149, s[8:9] offset:256
	v_add_u32_e32 v149, 0x80000, v148
	global_load_dwordx4 v[198:201], v149, s[8:9]
	global_load_dwordx4 v[202:205], v149, s[8:9] offset:256
	v_add_u32_e32 v149, 0x90000, v148
	global_load_dwordx4 v[206:209], v149, s[8:9]
	global_load_dwordx4 v[210:213], v149, s[8:9] offset:256
	v_add_u32_e32 v149, 0xa0000, v148
	global_load_dwordx4 v[214:217], v149, s[8:9]
	global_load_dwordx4 v[218:221], v149, s[8:9] offset:256
	v_add_u32_e32 v149, 0xb0000, v148
	global_load_dwordx4 v[222:225], v149, s[8:9]
	global_load_dwordx4 v[226:229], v149, s[8:9] offset:256
	s_waitcnt vmcnt(15)
	v_lshlrev_b32_e32 v230, 16, v154
	v_and_b32_e32 v154, 0xffff0000, v154
	v_lshlrev_b32_e32 v231, 16, v155
	v_and_b32_e32 v155, 0xffff0000, v155
	v_lshlrev_b32_e32 v232, 16, v156
	v_and_b32_e32 v156, 0xffff0000, v156
	v_lshlrev_b32_e32 v233, 16, v157
	v_and_b32_e32 v157, 0xffff0000, v157
	v_mul_f32_e32 v230, 0xbfb8aa3b, v230
	v_mul_f32_e32 v231, 0xbfb8aa3b, v231
	v_mul_f32_e32 v232, 0xbfb8aa3b, v232
	v_mul_f32_e32 v233, 0xbfb8aa3b, v233
	v_mul_f32_e32 v154, 0xbfb8aa3b, v154
	v_mul_f32_e32 v155, 0xbfb8aa3b, v155
	v_mul_f32_e32 v156, 0xbfb8aa3b, v156
	v_mul_f32_e32 v157, 0xbfb8aa3b, v157
	v_exp_f32_e32 v230, v230
	v_exp_f32_e32 v231, v231
	v_exp_f32_e32 v232, v232
	v_exp_f32_e32 v233, v233
	v_exp_f32_e32 v154, v154
	v_exp_f32_e32 v155, v155
	v_exp_f32_e32 v156, v156
	v_exp_f32_e32 v157, v157
	v_add_f32_e32 v230, 1.0, v230
	v_add_f32_e32 v231, 1.0, v231
	v_add_f32_e32 v232, 1.0, v232
	v_add_f32_e32 v233, 1.0, v233
	v_add_f32_e32 v154, 1.0, v154
	v_add_f32_e32 v155, 1.0, v155
	v_add_f32_e32 v156, 1.0, v156
	v_add_f32_e32 v157, 1.0, v157
	v_rcp_f32_e32 v230, v230
	v_rcp_f32_e32 v231, v231
	v_rcp_f32_e32 v232, v232
	v_rcp_f32_e32 v233, v233
	v_rcp_f32_e32 v154, v154
	v_rcp_f32_e32 v155, v155
	v_rcp_f32_e32 v156, v156
	v_rcp_f32_e32 v157, v157
	s_nop 0
	v_mul_f32_e32 v124, v124, v230
	v_mul_f32_e32 v125, v125, v154
	v_mul_f32_e32 v126, v126, v231
	v_mul_f32_e32 v127, v127, v155
	v_mul_f32_e32 v120, v120, v232
	v_mul_f32_e32 v121, v121, v156
	v_mul_f32_e32 v122, v122, v233
	v_mul_f32_e32 v123, v123, v157
	v_cvt_pk_bf16_f32 v124, v124, v125
	v_cvt_pk_bf16_f32 v125, v126, v127
	v_cvt_pk_bf16_f32 v126, v120, v121
	v_cvt_pk_bf16_f32 v127, v122, v123
	global_store_dwordx4 v148, v[124:127], s[12:13]
	s_waitcnt vmcnt(15)
	v_lshlrev_b32_e32 v230, 16, v158
	v_and_b32_e32 v158, 0xffff0000, v158
	v_lshlrev_b32_e32 v231, 16, v159
	v_and_b32_e32 v159, 0xffff0000, v159
	v_lshlrev_b32_e32 v232, 16, v160
	v_and_b32_e32 v160, 0xffff0000, v160
	v_lshlrev_b32_e32 v233, 16, v161
	v_and_b32_e32 v161, 0xffff0000, v161
	v_mul_f32_e32 v230, 0xbfb8aa3b, v230
	v_mul_f32_e32 v231, 0xbfb8aa3b, v231
	v_mul_f32_e32 v232, 0xbfb8aa3b, v232
	v_mul_f32_e32 v233, 0xbfb8aa3b, v233
	v_mul_f32_e32 v158, 0xbfb8aa3b, v158
	v_mul_f32_e32 v159, 0xbfb8aa3b, v159
	v_mul_f32_e32 v160, 0xbfb8aa3b, v160
	v_mul_f32_e32 v161, 0xbfb8aa3b, v161
	v_exp_f32_e32 v230, v230
	v_exp_f32_e32 v231, v231
	v_exp_f32_e32 v232, v232
	v_exp_f32_e32 v233, v233
	v_exp_f32_e32 v158, v158
	v_exp_f32_e32 v159, v159
	v_exp_f32_e32 v160, v160
	v_exp_f32_e32 v161, v161
	v_add_f32_e32 v230, 1.0, v230
	v_add_f32_e32 v231, 1.0, v231
	v_add_f32_e32 v232, 1.0, v232
	v_add_f32_e32 v233, 1.0, v233
	v_add_f32_e32 v158, 1.0, v158
	v_add_f32_e32 v159, 1.0, v159
	v_add_f32_e32 v160, 1.0, v160
	v_add_f32_e32 v161, 1.0, v161
	v_rcp_f32_e32 v230, v230
	v_rcp_f32_e32 v231, v231
	v_rcp_f32_e32 v232, v232
	v_rcp_f32_e32 v233, v233
	v_rcp_f32_e32 v158, v158
	v_rcp_f32_e32 v159, v159
	v_rcp_f32_e32 v160, v160
	v_rcp_f32_e32 v161, v161
	s_nop 0
	v_mul_f32_e32 v116, v116, v230
	v_mul_f32_e32 v117, v117, v158
	v_mul_f32_e32 v118, v118, v231
	v_mul_f32_e32 v119, v119, v159
	v_mul_f32_e32 v112, v112, v232
	v_mul_f32_e32 v113, v113, v160
	v_mul_f32_e32 v114, v114, v233
	v_mul_f32_e32 v115, v115, v161
	v_cvt_pk_bf16_f32 v116, v116, v117
	v_cvt_pk_bf16_f32 v117, v118, v119
	v_cvt_pk_bf16_f32 v118, v112, v113
	v_cvt_pk_bf16_f32 v119, v114, v115
	global_store_dwordx4 v148, v[116:119], s[12:13] offset:256
	s_waitcnt vmcnt(15)
	v_lshlrev_b32_e32 v230, 16, v162
	v_and_b32_e32 v162, 0xffff0000, v162
	v_lshlrev_b32_e32 v231, 16, v163
	v_and_b32_e32 v163, 0xffff0000, v163
	v_lshlrev_b32_e32 v232, 16, v164
	v_and_b32_e32 v164, 0xffff0000, v164
	v_lshlrev_b32_e32 v233, 16, v165
	v_and_b32_e32 v165, 0xffff0000, v165
	v_mul_f32_e32 v230, 0xbfb8aa3b, v230
	v_mul_f32_e32 v231, 0xbfb8aa3b, v231
	v_mul_f32_e32 v232, 0xbfb8aa3b, v232
	v_mul_f32_e32 v233, 0xbfb8aa3b, v233
	v_mul_f32_e32 v162, 0xbfb8aa3b, v162
	v_mul_f32_e32 v163, 0xbfb8aa3b, v163
	v_mul_f32_e32 v164, 0xbfb8aa3b, v164
	v_mul_f32_e32 v165, 0xbfb8aa3b, v165
	v_exp_f32_e32 v230, v230
	v_exp_f32_e32 v231, v231
	v_exp_f32_e32 v232, v232
	v_exp_f32_e32 v233, v233
	v_exp_f32_e32 v162, v162
	v_exp_f32_e32 v163, v163
	v_exp_f32_e32 v164, v164
	v_exp_f32_e32 v165, v165
	v_add_f32_e32 v230, 1.0, v230
	v_add_f32_e32 v231, 1.0, v231
	v_add_f32_e32 v232, 1.0, v232
	v_add_f32_e32 v233, 1.0, v233
	v_add_f32_e32 v162, 1.0, v162
	v_add_f32_e32 v163, 1.0, v163
	v_add_f32_e32 v164, 1.0, v164
	v_add_f32_e32 v165, 1.0, v165
	v_rcp_f32_e32 v230, v230
	v_rcp_f32_e32 v231, v231
	v_rcp_f32_e32 v232, v232
	v_rcp_f32_e32 v233, v233
	v_rcp_f32_e32 v162, v162
	v_rcp_f32_e32 v163, v163
	v_rcp_f32_e32 v164, v164
	v_rcp_f32_e32 v165, v165
	s_nop 0
	v_mul_f32_e32 v108, v108, v230
	v_mul_f32_e32 v109, v109, v162
	v_mul_f32_e32 v110, v110, v231
	v_mul_f32_e32 v111, v111, v163
	v_mul_f32_e32 v104, v104, v232
	v_mul_f32_e32 v105, v105, v164
	v_mul_f32_e32 v106, v106, v233
	v_mul_f32_e32 v107, v107, v165
	v_cvt_pk_bf16_f32 v108, v108, v109
	v_cvt_pk_bf16_f32 v109, v110, v111
	v_cvt_pk_bf16_f32 v110, v104, v105
	v_cvt_pk_bf16_f32 v111, v106, v107
	v_add_u32_e32 v149, 0x10000, v148
	global_store_dwordx4 v149, v[108:111], s[12:13]
	s_waitcnt vmcnt(15)
; __device__ __forceinline__ void store8(bf16_t* dst, const float* v) { u32x4 w; w.x = pk2(v[0], v[1]); w.y = pk2(v[2], v[3]); w.z = pk2(v[4], v[5]); w.w = pk2(v[6], v[7]); *(u32x4*)dst = w; }
; __device__ __forceinline__ void load8(const bf16_t* src, float* v) { const u32x4 w = *(const u32x4*)src; v[0] = bf_lo(w.x); v[1] = bf_hi(w.x); v[2] = bf_lo(w.y); v[3] = bf_hi(w.y); v[4] = bf_lo(w.z); v[5] = bf_hi(w.z); v[6] = bf_lo(w.w); v[7] = bf_hi(w.w); }
; __device__ __forceinline__ float sigmoidf_(float v) { return __builtin_amdgcn_rcpf(1.f + __builtin_amdgcn_exp2f(-v * LOG2E)); }
;     __device__ __forceinline__ void operator()(const pg8::f32x4 (&acc)[2][2][4][2], const pg8::Unit& u, int wr, int wc, int fr, int fq) const {
;     ...
;                     } else if constexpr (KIND == EK_MIX1) {
;                         const size_t off = (size_t)row * 2048 + pn * 256 + cl; float g[8]; load8(a.g0 + off, g);
; #pragma unroll
;                         for (int j = 0; j < 8; ++j) v[j] *= g[j];
;                         store8(a.o0 + off, v);
	v_lshlrev_b32_e32 v230, 16, v168
	v_and_b32_e32 v168, 0xffff0000, v168
	v_lshlrev_b32_e32 v231, 16, v169
	v_and_b32_e32 v169, 0xffff0000, v169
	v_lshlrev_b32_e32 v232, 16, v170
	v_and_b32_e32 v170, 0xffff0000, v170
	v_lshlrev_b32_e32 v233, 16, v171
	v_and_b32_e32 v171, 0xffff0000, v171
	v_mul_f32_e32 v230, 0xbfb8aa3b, v230
	v_mul_f32_e32 v231, 0xbfb8aa3b, v231
	v_mul_f32_e32 v232, 0xbfb8aa3b, v232
	v_mul_f32_e32 v233, 0xbfb8aa3b, v233
	v_mul_f32_e32 v168, 0xbfb8aa3b, v168
	v_mul_f32_e32 v169, 0xbfb8aa3b, v169
	v_mul_f32_e32 v170, 0xbfb8aa3b, v170
	v_mul_f32_e32 v171, 0xbfb8aa3b, v171
	v_exp_f32_e32 v230, v230
	v_exp_f32_e32 v231, v231
	v_exp_f32_e32 v232, v232
	v_exp_f32_e32 v233, v233
	v_exp_f32_e32 v168, v168
	v_exp_f32_e32 v169, v169
	v_exp_f32_e32 v170, v170
	v_exp_f32_e32 v171, v171
	v_add_f32_e32 v230, 1.0, v230
	v_add_f32_e32 v231, 1.0, v231
	v_add_f32_e32 v232, 1.0, v232
	v_add_f32_e32 v233, 1.0, v233
	v_add_f32_e32 v168, 1.0, v168
	v_add_f32_e32 v169, 1.0, v169
	v_add_f32_e32 v170, 1.0, v170
	v_add_f32_e32 v171, 1.0, v171
	v_rcp_f32_e32 v230, v230
	v_rcp_f32_e32 v231, v231
	v_rcp_f32_e32 v232, v232
	v_rcp_f32_e32 v233, v233
	v_rcp_f32_e32 v168, v168
	v_rcp_f32_e32 v169, v169
	v_rcp_f32_e32 v170, v170
	v_rcp_f32_e32 v171, v171
	s_nop 0
	v_mul_f32_e32 v100, v100, v230
	v_mul_f32_e32 v101, v101, v168
	v_mul_f32_e32 v102, v102, v231
	v_mul_f32_e32 v103, v103, v169
	v_mul_f32_e32 v96, v96, v232
	v_mul_f32_e32 v97, v97, v170
	v_mul_f32_e32 v98, v98, v233
	v_mul_f32_e32 v99, v99, v171
	v_cvt_pk_bf16_f32 v100, v100, v101
	v_cvt_pk_bf16_f32 v101, v102, v103
	v_cvt_pk_bf16_f32 v102, v96, v97
	v_cvt_pk_bf16_f32 v103, v98, v99
	global_store_dwordx4 v149, v[100:103], s[12:13] offset:256
	s_waitcnt vmcnt(15)
	v_lshlrev_b32_e32 v230, 16, v182
	v_and_b32_e32 v182, 0xffff0000, v182
	v_lshlrev_b32_e32 v231, 16, v183
	v_and_b32_e32 v183, 0xffff0000, v183
	v_lshlrev_b32_e32 v232, 16, v184
	v_and_b32_e32 v184, 0xffff0000, v184
	v_lshlrev_b32_e32 v233, 16, v185
	v_and_b32_e32 v185, 0xffff0000, v185
	v_mul_f32_e32 v230, 0xbfb8aa3b, v230
	v_mul_f32_e32 v231, 0xbfb8aa3b, v231
	v_mul_f32_e32 v232, 0xbfb8aa3b, v232
	v_mul_f32_e32 v233, 0xbfb8aa3b, v233
	v_mul_f32_e32 v182, 0xbfb8aa3b, v182
	v_mul_f32_e32 v183, 0xbfb8aa3b, v183
	v_mul_f32_e32 v184, 0xbfb8aa3b, v184
	v_mul_f32_e32 v185, 0xbfb8aa3b, v185
	v_exp_f32_e32 v230, v230
	v_exp_f32_e32 v231, v231
	v_exp_f32_e32 v232, v232
	v_exp_f32_e32 v233, v233
	v_exp_f32_e32 v182, v182
	v_exp_f32_e32 v183, v183
	v_exp_f32_e32 v184, v184
	v_exp_f32_e32 v185, v185
	v_add_f32_e32 v230, 1.0, v230
	v_add_f32_e32 v231, 1.0, v231
	v_add_f32_e32 v232, 1.0, v232
	v_add_f32_e32 v233, 1.0, v233
	v_add_f32_e32 v182, 1.0, v182
	v_add_f32_e32 v183, 1.0, v183
	v_add_f32_e32 v184, 1.0, v184
	v_add_f32_e32 v185, 1.0, v185
	v_rcp_f32_e32 v230, v230
	v_rcp_f32_e32 v231, v231
	v_rcp_f32_e32 v232, v232
	v_rcp_f32_e32 v233, v233
	v_rcp_f32_e32 v182, v182
	v_rcp_f32_e32 v183, v183
	v_rcp_f32_e32 v184, v184
	v_rcp_f32_e32 v185, v185
	s_nop 0
	v_mul_f32_e32 v92, v92, v230
	v_mul_f32_e32 v93, v93, v182
	v_mul_f32_e32 v94, v94, v231
	v_mul_f32_e32 v95, v95, v183
	v_mul_f32_e32 v88, v88, v232
	v_mul_f32_e32 v89, v89, v184
	v_mul_f32_e32 v90, v90, v233
	v_mul_f32_e32 v91, v91, v185
	v_cvt_pk_bf16_f32 v92, v92, v93
	v_cvt_pk_bf16_f32 v93, v94, v95
	v_cvt_pk_bf16_f32 v94, v88, v89
	v_cvt_pk_bf16_f32 v95, v90, v91
	v_add_u32_e32 v149, 0x20000, v148
	global_store_dwordx4 v149, v[92:95], s[12:13]
	s_waitcnt vmcnt(15)
	v_lshlrev_b32_e32 v230, 16, v186
	v_and_b32_e32 v186, 0xffff0000, v186
	v_lshlrev_b32_e32 v231, 16, v187
	v_and_b32_e32 v187, 0xffff0000, v187
	v_lshlrev_b32_e32 v232, 16, v188
	v_and_b32_e32 v188, 0xffff0000, v188
	v_lshlrev_b32_e32 v233, 16, v189
	v_and_b32_e32 v189, 0xffff0000, v189
	v_mul_f32_e32 v230, 0xbfb8aa3b, v230
	v_mul_f32_e32 v231, 0xbfb8aa3b, v231
	v_mul_f32_e32 v232, 0xbfb8aa3b, v232
	v_mul_f32_e32 v233, 0xbfb8aa3b, v233
	v_mul_f32_e32 v186, 0xbfb8aa3b, v186
	v_mul_f32_e32 v187, 0xbfb8aa3b, v187
	v_mul_f32_e32 v188, 0xbfb8aa3b, v188
	v_mul_f32_e32 v189, 0xbfb8aa3b, v189
	v_exp_f32_e32 v230, v230
	v_exp_f32_e32 v231, v231
	v_exp_f32_e32 v232, v232
	v_exp_f32_e32 v233, v233
	v_exp_f32_e32 v186, v186
	v_exp_f32_e32 v187, v187
	v_exp_f32_e32 v188, v188
	v_exp_f32_e32 v189, v189
	v_add_f32_e32 v230, 1.0, v230
	v_add_f32_e32 v231, 1.0, v231
	v_add_f32_e32 v232, 1.0, v232
	v_add_f32_e32 v233, 1.0, v233
	v_add_f32_e32 v186, 1.0, v186
	v_add_f32_e32 v187, 1.0, v187
	v_add_f32_e32 v188, 1.0, v188
	v_add_f32_e32 v189, 1.0, v189
	v_rcp_f32_e32 v230, v230
	v_rcp_f32_e32 v231, v231
	v_rcp_f32_e32 v232, v232
	v_rcp_f32_e32 v233, v233
	v_rcp_f32_e32 v186, v186
	v_rcp_f32_e32 v187, v187
	v_rcp_f32_e32 v188, v188
	v_rcp_f32_e32 v189, v189
	s_nop 0
	v_mul_f32_e32 v84, v84, v230
	v_mul_f32_e32 v85, v85, v186
	v_mul_f32_e32 v86, v86, v231
	v_mul_f32_e32 v87, v87, v187
	v_mul_f32_e32 v80, v80, v232
	v_mul_f32_e32 v81, v81, v188
	v_mul_f32_e32 v82, v82, v233
	v_mul_f32_e32 v83, v83, v189
	v_cvt_pk_bf16_f32 v84, v84, v85
	v_cvt_pk_bf16_f32 v85, v86, v87
	v_cvt_pk_bf16_f32 v86, v80, v81
	v_cvt_pk_bf16_f32 v87, v82, v83
	global_store_dwordx4 v149, v[84:87], s[12:13] offset:256
	s_waitcnt vmcnt(15)
; __device__ __forceinline__ void store8(bf16_t* dst, const float* v) { u32x4 w; w.x = pk2(v[0], v[1]); w.y = pk2(v[2], v[3]); w.z = pk2(v[4], v[5]); w.w = pk2(v[6], v[7]); *(u32x4*)dst = w; }
; __device__ __forceinline__ void load8(const bf16_t* src, float* v) { const u32x4 w = *(const u32x4*)src; v[0] = bf_lo(w.x); v[1] = bf_hi(w.x); v[2] = bf_lo(w.y); v[3] = bf_hi(w.y); v[4] = bf_lo(w.z); v[5] = bf_hi(w.z); v[6] = bf_lo(w.w); v[7] = bf_hi(w.w); }
; __device__ __forceinline__ float sigmoidf_(float v) { return __builtin_amdgcn_rcpf(1.f + __builtin_amdgcn_exp2f(-v * LOG2E)); }
;     __device__ __forceinline__ void operator()(const pg8::f32x4 (&acc)[2][2][4][2], const pg8::Unit& u, int wr, int wc, int fr, int fq) const {
;     ...
;                     } else if constexpr (KIND == EK_MIX1) {
;                         const size_t off = (size_t)row * 2048 + pn * 256 + cl; float g[8]; load8(a.g0 + off, g);
; #pragma unroll
;                         for (int j = 0; j < 8; ++j) v[j] *= g[j];
;                         store8(a.o0 + off, v);
	v_lshlrev_b32_e32 v230, 16, v190
	v_and_b32_e32 v190, 0xffff0000, v190
	v_lshlrev_b32_e32 v231, 16, v191
	v_and_b32_e32 v191, 0xffff0000, v191
	v_lshlrev_b32_e32 v232, 16, v192
	v_and_b32_e32 v192, 0xffff0000, v192
	v_lshlrev_b32_e32 v233, 16, v193
	v_and_b32_e32 v193, 0xffff0000, v193
	v_mul_f32_e32 v230, 0xbfb8aa3b, v230
	v_mul_f32_e32 v231, 0xbfb8aa3b, v231
	v_mul_f32_e32 v232, 0xbfb8aa3b, v232
	v_mul_f32_e32 v233, 0xbfb8aa3b, v233
	v_mul_f32_e32 v190, 0xbfb8aa3b, v190
	v_mul_f32_e32 v191, 0xbfb8aa3b, v191
	v_mul_f32_e32 v192, 0xbfb8aa3b, v192
	v_mul_f32_e32 v193, 0xbfb8aa3b, v193
	v_exp_f32_e32 v230, v230
	v_exp_f32_e32 v231, v231
	v_exp_f32_e32 v232, v232
	v_exp_f32_e32 v233, v233
	v_exp_f32_e32 v190, v190
	v_exp_f32_e32 v191, v191
	v_exp_f32_e32 v192, v192
	v_exp_f32_e32 v193, v193
	v_add_f32_e32 v230, 1.0, v230
	v_add_f32_e32 v231, 1.0, v231
	v_add_f32_e32 v232, 1.0, v232
	v_add_f32_e32 v233, 1.0, v233
	v_add_f32_e32 v190, 1.0, v190
	v_add_f32_e32 v191, 1.0, v191
	v_add_f32_e32 v192, 1.0, v192
	v_add_f32_e32 v193, 1.0, v193
	v_rcp_f32_e32 v230, v230
	v_rcp_f32_e32 v231, v231
	v_rcp_f32_e32 v232, v232
	v_rcp_f32_e32 v233, v233
	v_rcp_f32_e32 v190, v190
	v_rcp_f32_e32 v191, v191
	v_rcp_f32_e32 v192, v192
	v_rcp_f32_e32 v193, v193
	s_nop 0
	v_mul_f32_e32 v76, v76, v230
	v_mul_f32_e32 v77, v77, v190
	v_mul_f32_e32 v78, v78, v231
	v_mul_f32_e32 v79, v79, v191
	v_mul_f32_e32 v72, v72, v232
	v_mul_f32_e32 v73, v73, v192
	v_mul_f32_e32 v74, v74, v233
	v_mul_f32_e32 v75, v75, v193
	v_cvt_pk_bf16_f32 v76, v76, v77
	v_cvt_pk_bf16_f32 v77, v78, v79
	v_cvt_pk_bf16_f32 v78, v72, v73
	v_cvt_pk_bf16_f32 v79, v74, v75
	v_add_u32_e32 v149, 0x30000, v148
	global_store_dwordx4 v149, v[76:79], s[12:13]
	s_waitcnt vmcnt(15)
	v_lshlrev_b32_e32 v230, 16, v194
	v_and_b32_e32 v194, 0xffff0000, v194
	v_lshlrev_b32_e32 v231, 16, v195
	v_and_b32_e32 v195, 0xffff0000, v195
	v_lshlrev_b32_e32 v232, 16, v196
	v_and_b32_e32 v196, 0xffff0000, v196
	v_lshlrev_b32_e32 v233, 16, v197
	v_and_b32_e32 v197, 0xffff0000, v197
	v_mul_f32_e32 v230, 0xbfb8aa3b, v230
	v_mul_f32_e32 v231, 0xbfb8aa3b, v231
	v_mul_f32_e32 v232, 0xbfb8aa3b, v232
	v_mul_f32_e32 v233, 0xbfb8aa3b, v233
	v_mul_f32_e32 v194, 0xbfb8aa3b, v194
	v_mul_f32_e32 v195, 0xbfb8aa3b, v195
	v_mul_f32_e32 v196, 0xbfb8aa3b, v196
	v_mul_f32_e32 v197, 0xbfb8aa3b, v197
	v_exp_f32_e32 v230, v230
	v_exp_f32_e32 v231, v231
	v_exp_f32_e32 v232, v232
	v_exp_f32_e32 v233, v233
	v_exp_f32_e32 v194, v194
	v_exp_f32_e32 v195, v195
	v_exp_f32_e32 v196, v196
	v_exp_f32_e32 v197, v197
	v_add_f32_e32 v230, 1.0, v230
	v_add_f32_e32 v231, 1.0, v231
	v_add_f32_e32 v232, 1.0, v232
	v_add_f32_e32 v233, 1.0, v233
	v_add_f32_e32 v194, 1.0, v194
	v_add_f32_e32 v195, 1.0, v195
	v_add_f32_e32 v196, 1.0, v196
	v_add_f32_e32 v197, 1.0, v197
	v_rcp_f32_e32 v230, v230
	v_rcp_f32_e32 v231, v231
	v_rcp_f32_e32 v232, v232
	v_rcp_f32_e32 v233, v233
	v_rcp_f32_e32 v194, v194
	v_rcp_f32_e32 v195, v195
	v_rcp_f32_e32 v196, v196
	v_rcp_f32_e32 v197, v197
	s_nop 0
	v_mul_f32_e32 v68, v68, v230
	v_mul_f32_e32 v69, v69, v194
	v_mul_f32_e32 v70, v70, v231
	v_mul_f32_e32 v71, v71, v195
	v_mul_f32_e32 v64, v64, v232
	v_mul_f32_e32 v65, v65, v196
	v_mul_f32_e32 v66, v66, v233
	v_mul_f32_e32 v67, v67, v197
	v_cvt_pk_bf16_f32 v68, v68, v69
	v_cvt_pk_bf16_f32 v69, v70, v71
	v_cvt_pk_bf16_f32 v70, v64, v65
	v_cvt_pk_bf16_f32 v71, v66, v67
	global_store_dwordx4 v149, v[68:71], s[12:13] offset:256
	s_waitcnt vmcnt(15)
	v_lshlrev_b32_e32 v230, 16, v198
	v_and_b32_e32 v198, 0xffff0000, v198
	v_lshlrev_b32_e32 v231, 16, v199
	v_and_b32_e32 v199, 0xffff0000, v199
	v_lshlrev_b32_e32 v232, 16, v200
	v_and_b32_e32 v200, 0xffff0000, v200
	v_lshlrev_b32_e32 v233, 16, v201
	v_and_b32_e32 v201, 0xffff0000, v201
	v_mul_f32_e32 v230, 0xbfb8aa3b, v230
	v_mul_f32_e32 v231, 0xbfb8aa3b, v231
	v_mul_f32_e32 v232, 0xbfb8aa3b, v232
	v_mul_f32_e32 v233, 0xbfb8aa3b, v233
	v_mul_f32_e32 v198, 0xbfb8aa3b, v198
	v_mul_f32_e32 v199, 0xbfb8aa3b, v199
	v_mul_f32_e32 v200, 0xbfb8aa3b, v200
	v_mul_f32_e32 v201, 0xbfb8aa3b, v201
	v_exp_f32_e32 v230, v230
	v_exp_f32_e32 v231, v231
	v_exp_f32_e32 v232, v232
	v_exp_f32_e32 v233, v233
	v_exp_f32_e32 v198, v198
	v_exp_f32_e32 v199, v199
	v_exp_f32_e32 v200, v200
	v_exp_f32_e32 v201, v201
	v_add_f32_e32 v230, 1.0, v230
	v_add_f32_e32 v231, 1.0, v231
	v_add_f32_e32 v232, 1.0, v232
	v_add_f32_e32 v233, 1.0, v233
	v_add_f32_e32 v198, 1.0, v198
	v_add_f32_e32 v199, 1.0, v199
	v_add_f32_e32 v200, 1.0, v200
	v_add_f32_e32 v201, 1.0, v201
	v_rcp_f32_e32 v230, v230
	v_rcp_f32_e32 v231, v231
	v_rcp_f32_e32 v232, v232
	v_rcp_f32_e32 v233, v233
	v_rcp_f32_e32 v198, v198
	v_rcp_f32_e32 v199, v199
	v_rcp_f32_e32 v200, v200
	v_rcp_f32_e32 v201, v201
	s_nop 0
	v_mul_f32_e32 v60, v60, v230
	v_mul_f32_e32 v61, v61, v198
	v_mul_f32_e32 v62, v62, v231
	v_mul_f32_e32 v63, v63, v199
	v_mul_f32_e32 v56, v56, v232
	v_mul_f32_e32 v57, v57, v200
	v_mul_f32_e32 v58, v58, v233
	v_mul_f32_e32 v59, v59, v201
	v_cvt_pk_bf16_f32 v60, v60, v61
	v_cvt_pk_bf16_f32 v61, v62, v63
	v_cvt_pk_bf16_f32 v62, v56, v57
	v_cvt_pk_bf16_f32 v63, v58, v59
	v_add_u32_e32 v149, 0x80000, v148
	global_store_dwordx4 v149, v[60:63], s[12:13]
	s_waitcnt vmcnt(15)
; __device__ __forceinline__ void store8(bf16_t* dst, const float* v) { u32x4 w; w.x = pk2(v[0], v[1]); w.y = pk2(v[2], v[3]); w.z = pk2(v[4], v[5]); w.w = pk2(v[6], v[7]); *(u32x4*)dst = w; }
; __device__ __forceinline__ void load8(const bf16_t* src, float* v) { const u32x4 w = *(const u32x4*)src; v[0] = bf_lo(w.x); v[1] = bf_hi(w.x); v[2] = bf_lo(w.y); v[3] = bf_hi(w.y); v[4] = bf_lo(w.z); v[5] = bf_hi(w.z); v[6] = bf_lo(w.w); v[7] = bf_hi(w.w); }
; __device__ __forceinline__ float sigmoidf_(float v) { return __builtin_amdgcn_rcpf(1.f + __builtin_amdgcn_exp2f(-v * LOG2E)); }
;     __device__ __forceinline__ void operator()(const pg8::f32x4 (&acc)[2][2][4][2], const pg8::Unit& u, int wr, int wc, int fr, int fq) const {
;     ...
;                     } else if constexpr (KIND == EK_MIX1) {
;                         const size_t off = (size_t)row * 2048 + pn * 256 + cl; float g[8]; load8(a.g0 + off, g);
; #pragma unroll
;                         for (int j = 0; j < 8; ++j) v[j] *= g[j];
;                         store8(a.o0 + off, v);
	v_lshlrev_b32_e32 v230, 16, v202
	v_and_b32_e32 v202, 0xffff0000, v202
	v_lshlrev_b32_e32 v231, 16, v203
	v_and_b32_e32 v203, 0xffff0000, v203
	v_lshlrev_b32_e32 v232, 16, v204
	v_and_b32_e32 v204, 0xffff0000, v204
	v_lshlrev_b32_e32 v233, 16, v205
	v_and_b32_e32 v205, 0xffff0000, v205
	v_mul_f32_e32 v230, 0xbfb8aa3b, v230
	v_mul_f32_e32 v231, 0xbfb8aa3b, v231
	v_mul_f32_e32 v232, 0xbfb8aa3b, v232
	v_mul_f32_e32 v233, 0xbfb8aa3b, v233
	v_mul_f32_e32 v202, 0xbfb8aa3b, v202
	v_mul_f32_e32 v203, 0xbfb8aa3b, v203
	v_mul_f32_e32 v204, 0xbfb8aa3b, v204
	v_mul_f32_e32 v205, 0xbfb8aa3b, v205
	v_exp_f32_e32 v230, v230
	v_exp_f32_e32 v231, v231
	v_exp_f32_e32 v232, v232
	v_exp_f32_e32 v233, v233
	v_exp_f32_e32 v202, v202
	v_exp_f32_e32 v203, v203
	v_exp_f32_e32 v204, v204
	v_exp_f32_e32 v205, v205
	v_add_f32_e32 v230, 1.0, v230
	v_add_f32_e32 v231, 1.0, v231
	v_add_f32_e32 v232, 1.0, v232
	v_add_f32_e32 v233, 1.0, v233
	v_add_f32_e32 v202, 1.0, v202
	v_add_f32_e32 v203, 1.0, v203
	v_add_f32_e32 v204, 1.0, v204
	v_add_f32_e32 v205, 1.0, v205
	v_rcp_f32_e32 v230, v230
	v_rcp_f32_e32 v231, v231
	v_rcp_f32_e32 v232, v232
	v_rcp_f32_e32 v233, v233
	v_rcp_f32_e32 v202, v202
	v_rcp_f32_e32 v203, v203
	v_rcp_f32_e32 v204, v204
	v_rcp_f32_e32 v205, v205
	s_nop 0
	v_mul_f32_e32 v52, v52, v230
	v_mul_f32_e32 v53, v53, v202
	v_mul_f32_e32 v54, v54, v231
	v_mul_f32_e32 v55, v55, v203
	v_mul_f32_e32 v48, v48, v232
	v_mul_f32_e32 v49, v49, v204
	v_mul_f32_e32 v50, v50, v233
	v_mul_f32_e32 v51, v51, v205
	v_cvt_pk_bf16_f32 v52, v52, v53
	v_cvt_pk_bf16_f32 v53, v54, v55
	v_cvt_pk_bf16_f32 v54, v48, v49
	v_cvt_pk_bf16_f32 v55, v50, v51
	global_store_dwordx4 v149, v[52:55], s[12:13] offset:256
	s_waitcnt vmcnt(15)
	v_lshlrev_b32_e32 v230, 16, v206
	v_and_b32_e32 v206, 0xffff0000, v206
	v_lshlrev_b32_e32 v231, 16, v207
	v_and_b32_e32 v207, 0xffff0000, v207
	v_lshlrev_b32_e32 v232, 16, v208
	v_and_b32_e32 v208, 0xffff0000, v208
	v_lshlrev_b32_e32 v233, 16, v209
	v_and_b32_e32 v209, 0xffff0000, v209
	v_mul_f32_e32 v230, 0xbfb8aa3b, v230
	v_mul_f32_e32 v231, 0xbfb8aa3b, v231
	v_mul_f32_e32 v232, 0xbfb8aa3b, v232
	v_mul_f32_e32 v233, 0xbfb8aa3b, v233
	v_mul_f32_e32 v206, 0xbfb8aa3b, v206
	v_mul_f32_e32 v207, 0xbfb8aa3b, v207
	v_mul_f32_e32 v208, 0xbfb8aa3b, v208
	v_mul_f32_e32 v209, 0xbfb8aa3b, v209
	v_exp_f32_e32 v230, v230
	v_exp_f32_e32 v231, v231
	v_exp_f32_e32 v232, v232
	v_exp_f32_e32 v233, v233
	v_exp_f32_e32 v206, v206
	v_exp_f32_e32 v207, v207
	v_exp_f32_e32 v208, v208
	v_exp_f32_e32 v209, v209
	v_add_f32_e32 v230, 1.0, v230
	v_add_f32_e32 v231, 1.0, v231
	v_add_f32_e32 v232, 1.0, v232
	v_add_f32_e32 v233, 1.0, v233
	v_add_f32_e32 v206, 1.0, v206
	v_add_f32_e32 v207, 1.0, v207
	v_add_f32_e32 v208, 1.0, v208
	v_add_f32_e32 v209, 1.0, v209
	v_rcp_f32_e32 v230, v230
	v_rcp_f32_e32 v231, v231
	v_rcp_f32_e32 v232, v232
	v_rcp_f32_e32 v233, v233
	v_rcp_f32_e32 v206, v206
	v_rcp_f32_e32 v207, v207
	v_rcp_f32_e32 v208, v208
	v_rcp_f32_e32 v209, v209
	s_nop 0
	v_mul_f32_e32 v44, v44, v230
	v_mul_f32_e32 v45, v45, v206
	v_mul_f32_e32 v46, v46, v231
	v_mul_f32_e32 v47, v47, v207
	v_mul_f32_e32 v40, v40, v232
	v_mul_f32_e32 v41, v41, v208
	v_mul_f32_e32 v42, v42, v233
	v_mul_f32_e32 v43, v43, v209
	v_cvt_pk_bf16_f32 v44, v44, v45
	v_cvt_pk_bf16_f32 v45, v46, v47
	v_cvt_pk_bf16_f32 v46, v40, v41
	v_cvt_pk_bf16_f32 v47, v42, v43
	v_add_u32_e32 v149, 0x90000, v148
	global_store_dwordx4 v149, v[44:47], s[12:13]
	s_waitcnt vmcnt(15)
	v_lshlrev_b32_e32 v230, 16, v210
	v_and_b32_e32 v210, 0xffff0000, v210
	v_lshlrev_b32_e32 v231, 16, v211
	v_and_b32_e32 v211, 0xffff0000, v211
	v_lshlrev_b32_e32 v232, 16, v212
	v_and_b32_e32 v212, 0xffff0000, v212
	v_lshlrev_b32_e32 v233, 16, v213
	v_and_b32_e32 v213, 0xffff0000, v213
	v_mul_f32_e32 v230, 0xbfb8aa3b, v230
	v_mul_f32_e32 v231, 0xbfb8aa3b, v231
	v_mul_f32_e32 v232, 0xbfb8aa3b, v232
	v_mul_f32_e32 v233, 0xbfb8aa3b, v233
	v_mul_f32_e32 v210, 0xbfb8aa3b, v210
	v_mul_f32_e32 v211, 0xbfb8aa3b, v211
	v_mul_f32_e32 v212, 0xbfb8aa3b, v212
	v_mul_f32_e32 v213, 0xbfb8aa3b, v213
	v_exp_f32_e32 v230, v230
	v_exp_f32_e32 v231, v231
	v_exp_f32_e32 v232, v232
	v_exp_f32_e32 v233, v233
	v_exp_f32_e32 v210, v210
	v_exp_f32_e32 v211, v211
	v_exp_f32_e32 v212, v212
	v_exp_f32_e32 v213, v213
	v_add_f32_e32 v230, 1.0, v230
	v_add_f32_e32 v231, 1.0, v231
	v_add_f32_e32 v232, 1.0, v232
	v_add_f32_e32 v233, 1.0, v233
	v_add_f32_e32 v210, 1.0, v210
	v_add_f32_e32 v211, 1.0, v211
	v_add_f32_e32 v212, 1.0, v212
	v_add_f32_e32 v213, 1.0, v213
	v_rcp_f32_e32 v230, v230
	v_rcp_f32_e32 v231, v231
	v_rcp_f32_e32 v232, v232
	v_rcp_f32_e32 v233, v233
	v_rcp_f32_e32 v210, v210
	v_rcp_f32_e32 v211, v211
	v_rcp_f32_e32 v212, v212
	v_rcp_f32_e32 v213, v213
	s_nop 0
	v_mul_f32_e32 v36, v36, v230
	v_mul_f32_e32 v37, v37, v210
	v_mul_f32_e32 v38, v38, v231
	v_mul_f32_e32 v39, v39, v211
	v_mul_f32_e32 v32, v32, v232
	v_mul_f32_e32 v33, v33, v212
	v_mul_f32_e32 v34, v34, v233
	v_mul_f32_e32 v35, v35, v213
	v_cvt_pk_bf16_f32 v36, v36, v37
	v_cvt_pk_bf16_f32 v37, v38, v39
	v_cvt_pk_bf16_f32 v38, v32, v33
	v_cvt_pk_bf16_f32 v39, v34, v35
	global_store_dwordx4 v149, v[36:39], s[12:13] offset:256
	s_waitcnt vmcnt(15)
; __device__ __forceinline__ void store8(bf16_t* dst, const float* v) { u32x4 w; w.x = pk2(v[0], v[1]); w.y = pk2(v[2], v[3]); w.z = pk2(v[4], v[5]); w.w = pk2(v[6], v[7]); *(u32x4*)dst = w; }
; __device__ __forceinline__ void load8(const bf16_t* src, float* v) { const u32x4 w = *(const u32x4*)src; v[0] = bf_lo(w.x); v[1] = bf_hi(w.x); v[2] = bf_lo(w.y); v[3] = bf_hi(w.y); v[4] = bf_lo(w.z); v[5] = bf_hi(w.z); v[6] = bf_lo(w.w); v[7] = bf_hi(w.w); }
; __device__ __forceinline__ float sigmoidf_(float v) { return __builtin_amdgcn_rcpf(1.f + __builtin_amdgcn_exp2f(-v * LOG2E)); }
;     __device__ __forceinline__ void operator()(const pg8::f32x4 (&acc)[2][2][4][2], const pg8::Unit& u, int wr, int wc, int fr, int fq) const {
;     ...
;                     } else if constexpr (KIND == EK_MIX1) {
;                         const size_t off = (size_t)row * 2048 + pn * 256 + cl; float g[8]; load8(a.g0 + off, g);
; #pragma unroll
;                         for (int j = 0; j < 8; ++j) v[j] *= g[j];
;                         store8(a.o0 + off, v);
	v_lshlrev_b32_e32 v230, 16, v214
	v_and_b32_e32 v214, 0xffff0000, v214
	v_lshlrev_b32_e32 v231, 16, v215
	v_and_b32_e32 v215, 0xffff0000, v215
	v_lshlrev_b32_e32 v232, 16, v216
	v_and_b32_e32 v216, 0xffff0000, v216
	v_lshlrev_b32_e32 v233, 16, v217
	v_and_b32_e32 v217, 0xffff0000, v217
	v_mul_f32_e32 v230, 0xbfb8aa3b, v230
	v_mul_f32_e32 v231, 0xbfb8aa3b, v231
	v_mul_f32_e32 v232, 0xbfb8aa3b, v232
	v_mul_f32_e32 v233, 0xbfb8aa3b, v233
	v_mul_f32_e32 v214, 0xbfb8aa3b, v214
	v_mul_f32_e32 v215, 0xbfb8aa3b, v215
	v_mul_f32_e32 v216, 0xbfb8aa3b, v216
	v_mul_f32_e32 v217, 0xbfb8aa3b, v217
	v_exp_f32_e32 v230, v230
	v_exp_f32_e32 v231, v231
	v_exp_f32_e32 v232, v232
	v_exp_f32_e32 v233, v233
	v_exp_f32_e32 v214, v214
	v_exp_f32_e32 v215, v215
	v_exp_f32_e32 v216, v216
	v_exp_f32_e32 v217, v217
	v_add_f32_e32 v230, 1.0, v230
	v_add_f32_e32 v231, 1.0, v231
	v_add_f32_e32 v232, 1.0, v232
	v_add_f32_e32 v233, 1.0, v233
	v_add_f32_e32 v214, 1.0, v214
	v_add_f32_e32 v215, 1.0, v215
	v_add_f32_e32 v216, 1.0, v216
	v_add_f32_e32 v217, 1.0, v217
	v_rcp_f32_e32 v230, v230
	v_rcp_f32_e32 v231, v231
	v_rcp_f32_e32 v232, v232
	v_rcp_f32_e32 v233, v233
	v_rcp_f32_e32 v214, v214
	v_rcp_f32_e32 v215, v215
	v_rcp_f32_e32 v216, v216
	v_rcp_f32_e32 v217, v217
	s_nop 0
	v_mul_f32_e32 v28, v28, v230
	v_mul_f32_e32 v29, v29, v214
	v_mul_f32_e32 v30, v30, v231
	v_mul_f32_e32 v31, v31, v215
	v_mul_f32_e32 v24, v24, v232
	v_mul_f32_e32 v25, v25, v216
	v_mul_f32_e32 v26, v26, v233
	v_mul_f32_e32 v27, v27, v217
	v_cvt_pk_bf16_f32 v28, v28, v29
	v_cvt_pk_bf16_f32 v29, v30, v31
	v_cvt_pk_bf16_f32 v30, v24, v25
	v_cvt_pk_bf16_f32 v31, v26, v27
	v_add_u32_e32 v149, 0xa0000, v148
	global_store_dwordx4 v149, v[28:31], s[12:13]
	s_waitcnt vmcnt(15)
	v_lshlrev_b32_e32 v230, 16, v218
	v_and_b32_e32 v218, 0xffff0000, v218
	v_lshlrev_b32_e32 v231, 16, v219
	v_and_b32_e32 v219, 0xffff0000, v219
	v_lshlrev_b32_e32 v232, 16, v220
	v_and_b32_e32 v220, 0xffff0000, v220
	v_lshlrev_b32_e32 v233, 16, v221
	v_and_b32_e32 v221, 0xffff0000, v221
	v_mul_f32_e32 v230, 0xbfb8aa3b, v230
	v_mul_f32_e32 v231, 0xbfb8aa3b, v231
	v_mul_f32_e32 v232, 0xbfb8aa3b, v232
	v_mul_f32_e32 v233, 0xbfb8aa3b, v233
	v_mul_f32_e32 v218, 0xbfb8aa3b, v218
	v_mul_f32_e32 v219, 0xbfb8aa3b, v219
	v_mul_f32_e32 v220, 0xbfb8aa3b, v220
	v_mul_f32_e32 v221, 0xbfb8aa3b, v221
	v_exp_f32_e32 v230, v230
	v_exp_f32_e32 v231, v231
	v_exp_f32_e32 v232, v232
	v_exp_f32_e32 v233, v233
	v_exp_f32_e32 v218, v218
	v_exp_f32_e32 v219, v219
	v_exp_f32_e32 v220, v220
	v_exp_f32_e32 v221, v221
	v_add_f32_e32 v230, 1.0, v230
	v_add_f32_e32 v231, 1.0, v231
	v_add_f32_e32 v232, 1.0, v232
	v_add_f32_e32 v233, 1.0, v233
	v_add_f32_e32 v218, 1.0, v218
	v_add_f32_e32 v219, 1.0, v219
	v_add_f32_e32 v220, 1.0, v220
	v_add_f32_e32 v221, 1.0, v221
	v_rcp_f32_e32 v230, v230
	v_rcp_f32_e32 v231, v231
	v_rcp_f32_e32 v232, v232
	v_rcp_f32_e32 v233, v233
	v_rcp_f32_e32 v218, v218
	v_rcp_f32_e32 v219, v219
	v_rcp_f32_e32 v220, v220
	v_rcp_f32_e32 v221, v221
	s_nop 0
	v_mul_f32_e32 v20, v20, v230
	v_mul_f32_e32 v21, v21, v218
	v_mul_f32_e32 v22, v22, v231
	v_mul_f32_e32 v23, v23, v219
	v_mul_f32_e32 v16, v16, v232
	v_mul_f32_e32 v17, v17, v220
	v_mul_f32_e32 v18, v18, v233
	v_mul_f32_e32 v19, v19, v221
	v_cvt_pk_bf16_f32 v20, v20, v21
	v_cvt_pk_bf16_f32 v21, v22, v23
	v_cvt_pk_bf16_f32 v22, v16, v17
	v_cvt_pk_bf16_f32 v23, v18, v19
	global_store_dwordx4 v149, v[20:23], s[12:13] offset:256
	s_waitcnt vmcnt(15)
	v_lshlrev_b32_e32 v230, 16, v222
	v_and_b32_e32 v222, 0xffff0000, v222
	v_lshlrev_b32_e32 v231, 16, v223
	v_and_b32_e32 v223, 0xffff0000, v223
	v_lshlrev_b32_e32 v232, 16, v224
	v_and_b32_e32 v224, 0xffff0000, v224
	v_lshlrev_b32_e32 v233, 16, v225
	v_and_b32_e32 v225, 0xffff0000, v225
	v_mul_f32_e32 v230, 0xbfb8aa3b, v230
	v_mul_f32_e32 v231, 0xbfb8aa3b, v231
	v_mul_f32_e32 v232, 0xbfb8aa3b, v232
	v_mul_f32_e32 v233, 0xbfb8aa3b, v233
	v_mul_f32_e32 v222, 0xbfb8aa3b, v222
	v_mul_f32_e32 v223, 0xbfb8aa3b, v223
	v_mul_f32_e32 v224, 0xbfb8aa3b, v224
	v_mul_f32_e32 v225, 0xbfb8aa3b, v225
	v_exp_f32_e32 v230, v230
	v_exp_f32_e32 v231, v231
	v_exp_f32_e32 v232, v232
	v_exp_f32_e32 v233, v233
	v_exp_f32_e32 v222, v222
	v_exp_f32_e32 v223, v223
	v_exp_f32_e32 v224, v224
	v_exp_f32_e32 v225, v225
	v_add_f32_e32 v230, 1.0, v230
	v_add_f32_e32 v231, 1.0, v231
	v_add_f32_e32 v232, 1.0, v232
	v_add_f32_e32 v233, 1.0, v233
	v_add_f32_e32 v222, 1.0, v222
	v_add_f32_e32 v223, 1.0, v223
	v_add_f32_e32 v224, 1.0, v224
	v_add_f32_e32 v225, 1.0, v225
	v_rcp_f32_e32 v230, v230
	v_rcp_f32_e32 v231, v231
	v_rcp_f32_e32 v232, v232
	v_rcp_f32_e32 v233, v233
	v_rcp_f32_e32 v222, v222
	v_rcp_f32_e32 v223, v223
	v_rcp_f32_e32 v224, v224
	v_rcp_f32_e32 v225, v225
	s_nop 0
	v_mul_f32_e32 v12, v12, v230
	v_mul_f32_e32 v13, v13, v222
	v_mul_f32_e32 v14, v14, v231
	v_mul_f32_e32 v15, v15, v223
	v_mul_f32_e32 v8, v8, v232
	v_mul_f32_e32 v9, v9, v224
	v_mul_f32_e32 v10, v10, v233
	v_mul_f32_e32 v11, v11, v225
	v_cvt_pk_bf16_f32 v12, v12, v13
	v_cvt_pk_bf16_f32 v13, v14, v15
	v_cvt_pk_bf16_f32 v14, v8, v9
	v_cvt_pk_bf16_f32 v15, v10, v11
	v_add_u32_e32 v149, 0xb0000, v148
	global_store_dwordx4 v149, v[12:15], s[12:13]
	s_waitcnt vmcnt(15)
	v_lshlrev_b32_e32 v230, 16, v226
	v_and_b32_e32 v226, 0xffff0000, v226
	v_lshlrev_b32_e32 v231, 16, v227
	v_and_b32_e32 v227, 0xffff0000, v227
	v_lshlrev_b32_e32 v232, 16, v228
	v_and_b32_e32 v228, 0xffff0000, v228
	v_lshlrev_b32_e32 v233, 16, v229
	v_and_b32_e32 v229, 0xffff0000, v229
	v_mul_f32_e32 v230, 0xbfb8aa3b, v230
	v_mul_f32_e32 v231, 0xbfb8aa3b, v231
	v_mul_f32_e32 v232, 0xbfb8aa3b, v232
	v_mul_f32_e32 v233, 0xbfb8aa3b, v233
	v_mul_f32_e32 v226, 0xbfb8aa3b, v226
	v_mul_f32_e32 v227, 0xbfb8aa3b, v227
	v_mul_f32_e32 v228, 0xbfb8aa3b, v228
	v_mul_f32_e32 v229, 0xbfb8aa3b, v229
	v_exp_f32_e32 v230, v230
	v_exp_f32_e32 v231, v231
	v_exp_f32_e32 v232, v232
	v_exp_f32_e32 v233, v233
	v_exp_f32_e32 v226, v226
	v_exp_f32_e32 v227, v227
	v_exp_f32_e32 v228, v228
	v_exp_f32_e32 v229, v229
	v_add_f32_e32 v230, 1.0, v230
	v_add_f32_e32 v231, 1.0, v231
	v_add_f32_e32 v232, 1.0, v232
	v_add_f32_e32 v233, 1.0, v233
	v_add_f32_e32 v226, 1.0, v226
	v_add_f32_e32 v227, 1.0, v227
	v_add_f32_e32 v228, 1.0, v228
	v_add_f32_e32 v229, 1.0, v229
	v_rcp_f32_e32 v230, v230
	v_rcp_f32_e32 v231, v231
	v_rcp_f32_e32 v232, v232
	v_rcp_f32_e32 v233, v233
	v_rcp_f32_e32 v226, v226
	v_rcp_f32_e32 v227, v227
	v_rcp_f32_e32 v228, v228
	v_rcp_f32_e32 v229, v229
	s_nop 0
	v_mul_f32_e32 v4, v4, v230
	v_mul_f32_e32 v5, v5, v226
	v_mul_f32_e32 v6, v6, v231
	v_mul_f32_e32 v7, v7, v227
	v_mul_f32_e32 v0, v0, v232
	v_mul_f32_e32 v1, v1, v228
	v_mul_f32_e32 v2, v2, v233
	v_mul_f32_e32 v3, v3, v229
	v_cvt_pk_bf16_f32 v4, v4, v5
	v_cvt_pk_bf16_f32 v5, v6, v7
	v_cvt_pk_bf16_f32 v6, v0, v1
	v_cvt_pk_bf16_f32 v7, v2, v3
	global_store_dwordx4 v149, v[4:7], s[12:13] offset:256
	s_andn2_b64 vcc, exec, s[6:7]
	s_mov_b64 s[6:7], -1
	s_cbranch_vccnz .LBB0_1041
	s_andn2_b64 vcc, exec, s[10:11]
	s_cbranch_vccnz .LBB0_1040
	s_barrier
	s_branch .LBB0_1040

; __device__ __forceinline__ void store8(bf16_t* dst, const float* v) { u32x4 w; w.x = pk2(v[0], v[1]); w.y = pk2(v[2], v[3]); w.z = pk2(v[4], v[5]); w.w = pk2(v[6], v[7]); *(u32x4*)dst = w; }
; __device__ __forceinline__ void load8(const bf16_t* src, float* v) { const u32x4 w = *(const u32x4*)src; v[0] = bf_lo(w.x); v[1] = bf_hi(w.x); v[2] = bf_lo(w.y); v[3] = bf_hi(w.y); v[4] = bf_lo(w.z); v[5] = bf_hi(w.z); v[6] = bf_lo(w.w); v[7] = bf_hi(w.w); }
; __device__ __forceinline__ float sigmoidf_(float v) { return __builtin_amdgcn_rcpf(1.f + __builtin_amdgcn_exp2f(-v * LOG2E)); }
;     __device__ __forceinline__ void operator()(const pg8::f32x4 (&acc)[2][2][4][2], const pg8::Unit& u, int wr, int wc, int fr, int fq) const {
;     ...
;                     } else if constexpr (KIND == EK_MIX2) {
;                         const size_t off = (size_t)row * 2048 + pn * 256 + cl; float g[8], pr[8]; load8(a.g0 + off, g); load8(a.o0 + off, pr);
; #pragma unroll
;                         for (int j = 0; j < 8; ++j) v[j] = pr[j] + v[j] * g[j];
;                         store8(a.o0 + off, v);
.LBB0_1076:
	v_lshl_add_u32 v148, s26, 8, v137
	s_lshl_b32 s26, s27, 9
	v_lshlrev_b32_e32 v148, 12, v148
	v_lshl_add_u32 v149, v136, 1, s26
	v_add_u32_e32 v148, v148, v149
	global_load_dwordx4 v[154:157], v148, s[12:13]
	global_load_dwordx4 v[158:161], v148, s[10:11]
	global_load_dwordx4 v[162:165], v148, s[12:13] offset:256
	global_load_dwordx4 v[168:171], v148, s[10:11] offset:256
	v_add_u32_e32 v149, 0x10000, v148
	global_load_dwordx4 v[172:175], v149, s[12:13]
	global_load_dwordx4 v[182:185], v149, s[10:11]
	global_load_dwordx4 v[186:189], v149, s[12:13] offset:256
	global_load_dwordx4 v[190:193], v149, s[10:11] offset:256
	v_add_u32_e32 v149, 0x20000, v148
	global_load_dwordx4 v[194:197], v149, s[12:13]
	global_load_dwordx4 v[198:201], v149, s[10:11]
	global_load_dwordx4 v[202:205], v149, s[12:13] offset:256
	global_load_dwordx4 v[206:209], v149, s[10:11] offset:256
	v_add_u32_e32 v149, 0x30000, v148
	global_load_dwordx4 v[210:213], v149, s[12:13]
	global_load_dwordx4 v[214:217], v149, s[10:11]
	global_load_dwordx4 v[218:221], v149, s[12:13] offset:256
	global_load_dwordx4 v[222:225], v149, s[10:11] offset:256
	s_waitcnt vmcnt(14)
	v_lshlrev_b32_e32 v234, 16, v154
	v_and_b32_e32 v154, 0xffff0000, v154
	v_lshlrev_b32_e32 v235, 16, v155
	v_and_b32_e32 v155, 0xffff0000, v155
	v_lshlrev_b32_e32 v236, 16, v156
	v_and_b32_e32 v156, 0xffff0000, v156
	v_lshlrev_b32_e32 v237, 16, v157
	v_and_b32_e32 v157, 0xffff0000, v157
	v_mul_f32_e32 v234, 0xbfb8aa3b, v234
	v_mul_f32_e32 v235, 0xbfb8aa3b, v235
	v_mul_f32_e32 v236, 0xbfb8aa3b, v236
	v_mul_f32_e32 v237, 0xbfb8aa3b, v237
	v_mul_f32_e32 v154, 0xbfb8aa3b, v154
	v_mul_f32_e32 v155, 0xbfb8aa3b, v155
	v_mul_f32_e32 v156, 0xbfb8aa3b, v156
	v_mul_f32_e32 v157, 0xbfb8aa3b, v157
	v_exp_f32_e32 v234, v234
	v_exp_f32_e32 v235, v235
	v_exp_f32_e32 v236, v236
	v_exp_f32_e32 v237, v237
	v_exp_f32_e32 v154, v154
	v_exp_f32_e32 v155, v155
	v_exp_f32_e32 v156, v156
	v_exp_f32_e32 v157, v157
	v_add_f32_e32 v234, 1.0, v234
	v_add_f32_e32 v235, 1.0, v235
	v_add_f32_e32 v236, 1.0, v236
	v_add_f32_e32 v237, 1.0, v237
	v_add_f32_e32 v154, 1.0, v154
	v_add_f32_e32 v155, 1.0, v155
	v_add_f32_e32 v156, 1.0, v156
	v_add_f32_e32 v157, 1.0, v157
	v_rcp_f32_e32 v234, v234
	v_rcp_f32_e32 v235, v235
	v_rcp_f32_e32 v236, v236
	v_rcp_f32_e32 v237, v237
	v_rcp_f32_e32 v154, v154
	v_rcp_f32_e32 v155, v155
	v_rcp_f32_e32 v156, v156
	v_rcp_f32_e32 v157, v157
	v_lshlrev_b32_e32 v226, 16, v158
	v_and_b32_e32 v158, 0xffff0000, v158
	v_fma_f32 v124, v124, v234, v226
	v_fma_f32 v125, v125, v154, v158
	v_lshlrev_b32_e32 v227, 16, v159
	v_and_b32_e32 v159, 0xffff0000, v159
	v_fma_f32 v126, v126, v235, v227
	v_fma_f32 v127, v127, v155, v159
	v_lshlrev_b32_e32 v228, 16, v160
	v_and_b32_e32 v160, 0xffff0000, v160
	v_fma_f32 v120, v120, v236, v228
	v_fma_f32 v121, v121, v156, v160
	v_lshlrev_b32_e32 v229, 16, v161
	v_and_b32_e32 v161, 0xffff0000, v161
	v_fma_f32 v122, v122, v237, v229
	v_fma_f32 v123, v123, v157, v161
	v_cvt_pk_bf16_f32 v124, v124, v125
	v_cvt_pk_bf16_f32 v125, v126, v127
	v_cvt_pk_bf16_f32 v126, v120, v121
	v_cvt_pk_bf16_f32 v127, v122, v123
	global_store_dwordx4 v148, v[124:127], s[10:11]
	v_add_u32_e32 v149, 0x80000, v148
	global_load_dwordx4 v[154:157], v149, s[12:13]
	global_load_dwordx4 v[158:161], v149, s[10:11]
	s_waitcnt vmcnt(15)
	v_lshlrev_b32_e32 v234, 16, v162
	v_and_b32_e32 v162, 0xffff0000, v162
	v_lshlrev_b32_e32 v235, 16, v163
	v_and_b32_e32 v163, 0xffff0000, v163
	v_lshlrev_b32_e32 v236, 16, v164
	v_and_b32_e32 v164, 0xffff0000, v164
	v_lshlrev_b32_e32 v237, 16, v165
	v_and_b32_e32 v165, 0xffff0000, v165
	v_mul_f32_e32 v234, 0xbfb8aa3b, v234
	v_mul_f32_e32 v235, 0xbfb8aa3b, v235
	v_mul_f32_e32 v236, 0xbfb8aa3b, v236
	v_mul_f32_e32 v237, 0xbfb8aa3b, v237
	v_mul_f32_e32 v162, 0xbfb8aa3b, v162
	v_mul_f32_e32 v163, 0xbfb8aa3b, v163
	v_mul_f32_e32 v164, 0xbfb8aa3b, v164
	v_mul_f32_e32 v165, 0xbfb8aa3b, v165
	v_exp_f32_e32 v234, v234
	v_exp_f32_e32 v235, v235
	v_exp_f32_e32 v236, v236
	v_exp_f32_e32 v237, v237
	v_exp_f32_e32 v162, v162
	v_exp_f32_e32 v163, v163
	v_exp_f32_e32 v164, v164
	v_exp_f32_e32 v165, v165
	v_add_f32_e32 v234, 1.0, v234
	v_add_f32_e32 v235, 1.0, v235
	v_add_f32_e32 v236, 1.0, v236
	v_add_f32_e32 v237, 1.0, v237
	v_add_f32_e32 v162, 1.0, v162
	v_add_f32_e32 v163, 1.0, v163
	v_add_f32_e32 v164, 1.0, v164
	v_add_f32_e32 v165, 1.0, v165
	v_rcp_f32_e32 v234, v234
	v_rcp_f32_e32 v235, v235
	v_rcp_f32_e32 v236, v236
	v_rcp_f32_e32 v237, v237
	v_rcp_f32_e32 v162, v162
	v_rcp_f32_e32 v163, v163
	v_rcp_f32_e32 v164, v164
	v_rcp_f32_e32 v165, v165
	v_lshlrev_b32_e32 v226, 16, v168
	v_and_b32_e32 v168, 0xffff0000, v168
	v_fma_f32 v116, v116, v234, v226
	v_fma_f32 v117, v117, v162, v168
	v_lshlrev_b32_e32 v227, 16, v169
	v_and_b32_e32 v169, 0xffff0000, v169
	v_fma_f32 v118, v118, v235, v227
	v_fma_f32 v119, v119, v163, v169
	v_lshlrev_b32_e32 v228, 16, v170
	v_and_b32_e32 v170, 0xffff0000, v170
	v_fma_f32 v112, v112, v236, v228
	v_fma_f32 v113, v113, v164, v170
	v_lshlrev_b32_e32 v229, 16, v171
	v_and_b32_e32 v171, 0xffff0000, v171
	v_fma_f32 v114, v114, v237, v229
	v_fma_f32 v115, v115, v165, v171
	v_cvt_pk_bf16_f32 v116, v116, v117
	v_cvt_pk_bf16_f32 v117, v118, v119
	v_cvt_pk_bf16_f32 v118, v112, v113
	v_cvt_pk_bf16_f32 v119, v114, v115
	global_store_dwordx4 v148, v[116:119], s[10:11] offset:256
	global_load_dwordx4 v[162:165], v149, s[12:13] offset:256
	global_load_dwordx4 v[168:171], v149, s[10:11] offset:256
	s_waitcnt vmcnt(16)
; __device__ __forceinline__ void store8(bf16_t* dst, const float* v) { u32x4 w; w.x = pk2(v[0], v[1]); w.y = pk2(v[2], v[3]); w.z = pk2(v[4], v[5]); w.w = pk2(v[6], v[7]); *(u32x4*)dst = w; }
; __device__ __forceinline__ void load8(const bf16_t* src, float* v) { const u32x4 w = *(const u32x4*)src; v[0] = bf_lo(w.x); v[1] = bf_hi(w.x); v[2] = bf_lo(w.y); v[3] = bf_hi(w.y); v[4] = bf_lo(w.z); v[5] = bf_hi(w.z); v[6] = bf_lo(w.w); v[7] = bf_hi(w.w); }
; __device__ __forceinline__ float sigmoidf_(float v) { return __builtin_amdgcn_rcpf(1.f + __builtin_amdgcn_exp2f(-v * LOG2E)); }
;     __device__ __forceinline__ void operator()(const pg8::f32x4 (&acc)[2][2][4][2], const pg8::Unit& u, int wr, int wc, int fr, int fq) const {
;     ...
;                     } else if constexpr (KIND == EK_MIX2) {
;                         const size_t off = (size_t)row * 2048 + pn * 256 + cl; float g[8], pr[8]; load8(a.g0 + off, g); load8(a.o0 + off, pr);
; #pragma unroll
;                         for (int j = 0; j < 8; ++j) v[j] = pr[j] + v[j] * g[j];
;                         store8(a.o0 + off, v);
	v_lshlrev_b32_e32 v234, 16, v172
	v_and_b32_e32 v172, 0xffff0000, v172
	v_lshlrev_b32_e32 v235, 16, v173
	v_and_b32_e32 v173, 0xffff0000, v173
	v_lshlrev_b32_e32 v236, 16, v174
	v_and_b32_e32 v174, 0xffff0000, v174
	v_lshlrev_b32_e32 v237, 16, v175
	v_and_b32_e32 v175, 0xffff0000, v175
	v_mul_f32_e32 v234, 0xbfb8aa3b, v234
	v_mul_f32_e32 v235, 0xbfb8aa3b, v235
	v_mul_f32_e32 v236, 0xbfb8aa3b, v236
	v_mul_f32_e32 v237, 0xbfb8aa3b, v237
	v_mul_f32_e32 v172, 0xbfb8aa3b, v172
	v_mul_f32_e32 v173, 0xbfb8aa3b, v173
	v_mul_f32_e32 v174, 0xbfb8aa3b, v174
	v_mul_f32_e32 v175, 0xbfb8aa3b, v175
	v_exp_f32_e32 v234, v234
	v_exp_f32_e32 v235, v235
	v_exp_f32_e32 v236, v236
	v_exp_f32_e32 v237, v237
	v_exp_f32_e32 v172, v172
	v_exp_f32_e32 v173, v173
	v_exp_f32_e32 v174, v174
	v_exp_f32_e32 v175, v175
	v_add_f32_e32 v234, 1.0, v234
	v_add_f32_e32 v235, 1.0, v235
	v_add_f32_e32 v236, 1.0, v236
	v_add_f32_e32 v237, 1.0, v237
	v_add_f32_e32 v172, 1.0, v172
	v_add_f32_e32 v173, 1.0, v173
	v_add_f32_e32 v174, 1.0, v174
	v_add_f32_e32 v175, 1.0, v175
	v_rcp_f32_e32 v234, v234
	v_rcp_f32_e32 v235, v235
	v_rcp_f32_e32 v236, v236
	v_rcp_f32_e32 v237, v237
	v_rcp_f32_e32 v172, v172
	v_rcp_f32_e32 v173, v173
	v_rcp_f32_e32 v174, v174
	v_rcp_f32_e32 v175, v175
	v_lshlrev_b32_e32 v226, 16, v182
	v_and_b32_e32 v182, 0xffff0000, v182
	v_fma_f32 v108, v108, v234, v226
	v_fma_f32 v109, v109, v172, v182
	v_lshlrev_b32_e32 v227, 16, v183
	v_and_b32_e32 v183, 0xffff0000, v183
	v_fma_f32 v110, v110, v235, v227
	v_fma_f32 v111, v111, v173, v183
	v_lshlrev_b32_e32 v228, 16, v184
	v_and_b32_e32 v184, 0xffff0000, v184
	v_fma_f32 v104, v104, v236, v228
	v_fma_f32 v105, v105, v174, v184
	v_lshlrev_b32_e32 v229, 16, v185
	v_and_b32_e32 v185, 0xffff0000, v185
	v_fma_f32 v106, v106, v237, v229
	v_fma_f32 v107, v107, v175, v185
	v_cvt_pk_bf16_f32 v108, v108, v109
	v_cvt_pk_bf16_f32 v109, v110, v111
	v_cvt_pk_bf16_f32 v110, v104, v105
	v_cvt_pk_bf16_f32 v111, v106, v107
	v_add_u32_e32 v153, 0x10000, v148
	global_store_dwordx4 v153, v[108:111], s[10:11]
	v_add_u32_e32 v149, 0x90000, v148
	global_load_dwordx4 v[172:175], v149, s[12:13]
	global_load_dwordx4 v[182:185], v149, s[10:11]
	s_waitcnt vmcnt(17)
	v_lshlrev_b32_e32 v234, 16, v186
	v_and_b32_e32 v186, 0xffff0000, v186
	v_lshlrev_b32_e32 v235, 16, v187
	v_and_b32_e32 v187, 0xffff0000, v187
	v_lshlrev_b32_e32 v236, 16, v188
	v_and_b32_e32 v188, 0xffff0000, v188
	v_lshlrev_b32_e32 v237, 16, v189
	v_and_b32_e32 v189, 0xffff0000, v189
	v_mul_f32_e32 v234, 0xbfb8aa3b, v234
	v_mul_f32_e32 v235, 0xbfb8aa3b, v235
	v_mul_f32_e32 v236, 0xbfb8aa3b, v236
	v_mul_f32_e32 v237, 0xbfb8aa3b, v237
	v_mul_f32_e32 v186, 0xbfb8aa3b, v186
	v_mul_f32_e32 v187, 0xbfb8aa3b, v187
	v_mul_f32_e32 v188, 0xbfb8aa3b, v188
	v_mul_f32_e32 v189, 0xbfb8aa3b, v189
	v_exp_f32_e32 v234, v234
	v_exp_f32_e32 v235, v235
	v_exp_f32_e32 v236, v236
	v_exp_f32_e32 v237, v237
	v_exp_f32_e32 v186, v186
	v_exp_f32_e32 v187, v187
	v_exp_f32_e32 v188, v188
	v_exp_f32_e32 v189, v189
	v_add_f32_e32 v234, 1.0, v234
	v_add_f32_e32 v235, 1.0, v235
	v_add_f32_e32 v236, 1.0, v236
	v_add_f32_e32 v237, 1.0, v237
	v_add_f32_e32 v186, 1.0, v186
	v_add_f32_e32 v187, 1.0, v187
	v_add_f32_e32 v188, 1.0, v188
	v_add_f32_e32 v189, 1.0, v189
	v_rcp_f32_e32 v234, v234
	v_rcp_f32_e32 v235, v235
	v_rcp_f32_e32 v236, v236
	v_rcp_f32_e32 v237, v237
	v_rcp_f32_e32 v186, v186
	v_rcp_f32_e32 v187, v187
	v_rcp_f32_e32 v188, v188
	v_rcp_f32_e32 v189, v189
	v_lshlrev_b32_e32 v226, 16, v190
	v_and_b32_e32 v190, 0xffff0000, v190
	v_fma_f32 v100, v100, v234, v226
	v_fma_f32 v101, v101, v186, v190
	v_lshlrev_b32_e32 v227, 16, v191
	v_and_b32_e32 v191, 0xffff0000, v191
	v_fma_f32 v102, v102, v235, v227
	v_fma_f32 v103, v103, v187, v191
	v_lshlrev_b32_e32 v228, 16, v192
	v_and_b32_e32 v192, 0xffff0000, v192
	v_fma_f32 v96, v96, v236, v228
	v_fma_f32 v97, v97, v188, v192
	v_lshlrev_b32_e32 v229, 16, v193
	v_and_b32_e32 v193, 0xffff0000, v193
	v_fma_f32 v98, v98, v237, v229
	v_fma_f32 v99, v99, v189, v193
	v_cvt_pk_bf16_f32 v100, v100, v101
	v_cvt_pk_bf16_f32 v101, v102, v103
	v_cvt_pk_bf16_f32 v102, v96, v97
	v_cvt_pk_bf16_f32 v103, v98, v99
	global_store_dwordx4 v153, v[100:103], s[10:11] offset:256
	global_load_dwordx4 v[186:189], v149, s[12:13] offset:256
	global_load_dwordx4 v[190:193], v149, s[10:11] offset:256
	s_waitcnt vmcnt(18)
	v_lshlrev_b32_e32 v234, 16, v194
	v_and_b32_e32 v194, 0xffff0000, v194
	v_lshlrev_b32_e32 v235, 16, v195
	v_and_b32_e32 v195, 0xffff0000, v195
	v_lshlrev_b32_e32 v236, 16, v196
	v_and_b32_e32 v196, 0xffff0000, v196
	v_lshlrev_b32_e32 v237, 16, v197
	v_and_b32_e32 v197, 0xffff0000, v197
	v_mul_f32_e32 v234, 0xbfb8aa3b, v234
	v_mul_f32_e32 v235, 0xbfb8aa3b, v235
	v_mul_f32_e32 v236, 0xbfb8aa3b, v236
	v_mul_f32_e32 v237, 0xbfb8aa3b, v237
	v_mul_f32_e32 v194, 0xbfb8aa3b, v194
	v_mul_f32_e32 v195, 0xbfb8aa3b, v195
	v_mul_f32_e32 v196, 0xbfb8aa3b, v196
	v_mul_f32_e32 v197, 0xbfb8aa3b, v197
	v_exp_f32_e32 v234, v234
	v_exp_f32_e32 v235, v235
	v_exp_f32_e32 v236, v236
	v_exp_f32_e32 v237, v237
	v_exp_f32_e32 v194, v194
	v_exp_f32_e32 v195, v195
	v_exp_f32_e32 v196, v196
	v_exp_f32_e32 v197, v197
	v_add_f32_e32 v234, 1.0, v234
	v_add_f32_e32 v235, 1.0, v235
	v_add_f32_e32 v236, 1.0, v236
	v_add_f32_e32 v237, 1.0, v237
	v_add_f32_e32 v194, 1.0, v194
	v_add_f32_e32 v195, 1.0, v195
	v_add_f32_e32 v196, 1.0, v196
	v_add_f32_e32 v197, 1.0, v197
	v_rcp_f32_e32 v234, v234
	v_rcp_f32_e32 v235, v235
	v_rcp_f32_e32 v236, v236
	v_rcp_f32_e32 v237, v237
	v_rcp_f32_e32 v194, v194
	v_rcp_f32_e32 v195, v195
	v_rcp_f32_e32 v196, v196
	v_rcp_f32_e32 v197, v197
	v_lshlrev_b32_e32 v226, 16, v198
	v_and_b32_e32 v198, 0xffff0000, v198
	v_fma_f32 v92, v92, v234, v226
	v_fma_f32 v93, v93, v194, v198
	v_lshlrev_b32_e32 v227, 16, v199
	v_and_b32_e32 v199, 0xffff0000, v199
	v_fma_f32 v94, v94, v235, v227
	v_fma_f32 v95, v95, v195, v199
	v_lshlrev_b32_e32 v228, 16, v200
	v_and_b32_e32 v200, 0xffff0000, v200
	v_fma_f32 v88, v88, v236, v228
	v_fma_f32 v89, v89, v196, v200
	v_lshlrev_b32_e32 v229, 16, v201
	v_and_b32_e32 v201, 0xffff0000, v201
	v_fma_f32 v90, v90, v237, v229
	v_fma_f32 v91, v91, v197, v201
	v_cvt_pk_bf16_f32 v92, v92, v93
	v_cvt_pk_bf16_f32 v93, v94, v95
	v_cvt_pk_bf16_f32 v94, v88, v89
	v_cvt_pk_bf16_f32 v95, v90, v91
	v_add_u32_e32 v153, 0x20000, v148
	global_store_dwordx4 v153, v[92:95], s[10:11]
	v_add_u32_e32 v149, 0xa0000, v148
	global_load_dwordx4 v[194:197], v149, s[12:13]
	global_load_dwordx4 v[198:201], v149, s[10:11]
	s_waitcnt vmcnt(19)
; __device__ __forceinline__ void store8(bf16_t* dst, const float* v) { u32x4 w; w.x = pk2(v[0], v[1]); w.y = pk2(v[2], v[3]); w.z = pk2(v[4], v[5]); w.w = pk2(v[6], v[7]); *(u32x4*)dst = w; }
; __device__ __forceinline__ void load8(const bf16_t* src, float* v) { const u32x4 w = *(const u32x4*)src; v[0] = bf_lo(w.x); v[1] = bf_hi(w.x); v[2] = bf_lo(w.y); v[3] = bf_hi(w.y); v[4] = bf_lo(w.z); v[5] = bf_hi(w.z); v[6] = bf_lo(w.w); v[7] = bf_hi(w.w); }
; __device__ __forceinline__ float sigmoidf_(float v) { return __builtin_amdgcn_rcpf(1.f + __builtin_amdgcn_exp2f(-v * LOG2E)); }
;     __device__ __forceinline__ void operator()(const pg8::f32x4 (&acc)[2][2][4][2], const pg8::Unit& u, int wr, int wc, int fr, int fq) const {
;     ...
;                     } else if constexpr (KIND == EK_MIX2) {
;                         const size_t off = (size_t)row * 2048 + pn * 256 + cl; float g[8], pr[8]; load8(a.g0 + off, g); load8(a.o0 + off, pr);
; #pragma unroll
;                         for (int j = 0; j < 8; ++j) v[j] = pr[j] + v[j] * g[j];
;                         store8(a.o0 + off, v);
	v_lshlrev_b32_e32 v234, 16, v202
	v_and_b32_e32 v202, 0xffff0000, v202
	v_lshlrev_b32_e32 v235, 16, v203
	v_and_b32_e32 v203, 0xffff0000, v203
	v_lshlrev_b32_e32 v236, 16, v204
	v_and_b32_e32 v204, 0xffff0000, v204
	v_lshlrev_b32_e32 v237, 16, v205
	v_and_b32_e32 v205, 0xffff0000, v205
	v_mul_f32_e32 v234, 0xbfb8aa3b, v234
	v_mul_f32_e32 v235, 0xbfb8aa3b, v235
	v_mul_f32_e32 v236, 0xbfb8aa3b, v236
	v_mul_f32_e32 v237, 0xbfb8aa3b, v237
	v_mul_f32_e32 v202, 0xbfb8aa3b, v202
	v_mul_f32_e32 v203, 0xbfb8aa3b, v203
	v_mul_f32_e32 v204, 0xbfb8aa3b, v204
	v_mul_f32_e32 v205, 0xbfb8aa3b, v205
	v_exp_f32_e32 v234, v234
	v_exp_f32_e32 v235, v235
	v_exp_f32_e32 v236, v236
	v_exp_f32_e32 v237, v237
	v_exp_f32_e32 v202, v202
	v_exp_f32_e32 v203, v203
	v_exp_f32_e32 v204, v204
	v_exp_f32_e32 v205, v205
	v_add_f32_e32 v234, 1.0, v234
	v_add_f32_e32 v235, 1.0, v235
	v_add_f32_e32 v236, 1.0, v236
	v_add_f32_e32 v237, 1.0, v237
	v_add_f32_e32 v202, 1.0, v202
	v_add_f32_e32 v203, 1.0, v203
	v_add_f32_e32 v204, 1.0, v204
	v_add_f32_e32 v205, 1.0, v205
	v_rcp_f32_e32 v234, v234
	v_rcp_f32_e32 v235, v235
	v_rcp_f32_e32 v236, v236
	v_rcp_f32_e32 v237, v237
	v_rcp_f32_e32 v202, v202
	v_rcp_f32_e32 v203, v203
	v_rcp_f32_e32 v204, v204
	v_rcp_f32_e32 v205, v205
	v_lshlrev_b32_e32 v226, 16, v206
	v_and_b32_e32 v206, 0xffff0000, v206
	v_fma_f32 v84, v84, v234, v226
	v_fma_f32 v85, v85, v202, v206
	v_lshlrev_b32_e32 v227, 16, v207
	v_and_b32_e32 v207, 0xffff0000, v207
	v_fma_f32 v86, v86, v235, v227
	v_fma_f32 v87, v87, v203, v207
	v_lshlrev_b32_e32 v228, 16, v208
	v_and_b32_e32 v208, 0xffff0000, v208
	v_fma_f32 v80, v80, v236, v228
	v_fma_f32 v81, v81, v204, v208
	v_lshlrev_b32_e32 v229, 16, v209
	v_and_b32_e32 v209, 0xffff0000, v209
	v_fma_f32 v82, v82, v237, v229
	v_fma_f32 v83, v83, v205, v209
	v_cvt_pk_bf16_f32 v84, v84, v85
	v_cvt_pk_bf16_f32 v85, v86, v87
	v_cvt_pk_bf16_f32 v86, v80, v81
	v_cvt_pk_bf16_f32 v87, v82, v83
	global_store_dwordx4 v153, v[84:87], s[10:11] offset:256
	global_load_dwordx4 v[202:205], v149, s[12:13] offset:256
	global_load_dwordx4 v[206:209], v149, s[10:11] offset:256
	s_waitcnt vmcnt(20)
	v_lshlrev_b32_e32 v234, 16, v210
	v_and_b32_e32 v210, 0xffff0000, v210
	v_lshlrev_b32_e32 v235, 16, v211
	v_and_b32_e32 v211, 0xffff0000, v211
	v_lshlrev_b32_e32 v236, 16, v212
	v_and_b32_e32 v212, 0xffff0000, v212
	v_lshlrev_b32_e32 v237, 16, v213
	v_and_b32_e32 v213, 0xffff0000, v213
	v_mul_f32_e32 v234, 0xbfb8aa3b, v234
	v_mul_f32_e32 v235, 0xbfb8aa3b, v235
	v_mul_f32_e32 v236, 0xbfb8aa3b, v236
	v_mul_f32_e32 v237, 0xbfb8aa3b, v237
	v_mul_f32_e32 v210, 0xbfb8aa3b, v210
	v_mul_f32_e32 v211, 0xbfb8aa3b, v211
	v_mul_f32_e32 v212, 0xbfb8aa3b, v212
	v_mul_f32_e32 v213, 0xbfb8aa3b, v213
	v_exp_f32_e32 v234, v234
	v_exp_f32_e32 v235, v235
	v_exp_f32_e32 v236, v236
	v_exp_f32_e32 v237, v237
	v_exp_f32_e32 v210, v210
	v_exp_f32_e32 v211, v211
	v_exp_f32_e32 v212, v212
	v_exp_f32_e32 v213, v213
	v_add_f32_e32 v234, 1.0, v234
	v_add_f32_e32 v235, 1.0, v235
	v_add_f32_e32 v236, 1.0, v236
	v_add_f32_e32 v237, 1.0, v237
	v_add_f32_e32 v210, 1.0, v210
	v_add_f32_e32 v211, 1.0, v211
	v_add_f32_e32 v212, 1.0, v212
	v_add_f32_e32 v213, 1.0, v213
	v_rcp_f32_e32 v234, v234
	v_rcp_f32_e32 v235, v235
	v_rcp_f32_e32 v236, v236
	v_rcp_f32_e32 v237, v237
	v_rcp_f32_e32 v210, v210
	v_rcp_f32_e32 v211, v211
	v_rcp_f32_e32 v212, v212
	v_rcp_f32_e32 v213, v213
	v_lshlrev_b32_e32 v226, 16, v214
	v_and_b32_e32 v214, 0xffff0000, v214
	v_fma_f32 v76, v76, v234, v226
	v_fma_f32 v77, v77, v210, v214
	v_lshlrev_b32_e32 v227, 16, v215
	v_and_b32_e32 v215, 0xffff0000, v215
	v_fma_f32 v78, v78, v235, v227
	v_fma_f32 v79, v79, v211, v215
	v_lshlrev_b32_e32 v228, 16, v216
	v_and_b32_e32 v216, 0xffff0000, v216
	v_fma_f32 v72, v72, v236, v228
	v_fma_f32 v73, v73, v212, v216
	v_lshlrev_b32_e32 v229, 16, v217
	v_and_b32_e32 v217, 0xffff0000, v217
	v_fma_f32 v74, v74, v237, v229
	v_fma_f32 v75, v75, v213, v217
	v_cvt_pk_bf16_f32 v76, v76, v77
	v_cvt_pk_bf16_f32 v77, v78, v79
	v_cvt_pk_bf16_f32 v78, v72, v73
	v_cvt_pk_bf16_f32 v79, v74, v75
	v_add_u32_e32 v153, 0x30000, v148
	global_store_dwordx4 v153, v[76:79], s[10:11]
	v_add_u32_e32 v149, 0xb0000, v148
	global_load_dwordx4 v[210:213], v149, s[12:13]
	global_load_dwordx4 v[214:217], v149, s[10:11]
	s_waitcnt vmcnt(21)
	v_lshlrev_b32_e32 v234, 16, v218
	v_and_b32_e32 v218, 0xffff0000, v218
	v_lshlrev_b32_e32 v235, 16, v219
	v_and_b32_e32 v219, 0xffff0000, v219
	v_lshlrev_b32_e32 v236, 16, v220
	v_and_b32_e32 v220, 0xffff0000, v220
	v_lshlrev_b32_e32 v237, 16, v221
	v_and_b32_e32 v221, 0xffff0000, v221
	v_mul_f32_e32 v234, 0xbfb8aa3b, v234
	v_mul_f32_e32 v235, 0xbfb8aa3b, v235
	v_mul_f32_e32 v236, 0xbfb8aa3b, v236
	v_mul_f32_e32 v237, 0xbfb8aa3b, v237
	v_mul_f32_e32 v218, 0xbfb8aa3b, v218
	v_mul_f32_e32 v219, 0xbfb8aa3b, v219
	v_mul_f32_e32 v220, 0xbfb8aa3b, v220
	v_mul_f32_e32 v221, 0xbfb8aa3b, v221
	v_exp_f32_e32 v234, v234
	v_exp_f32_e32 v235, v235
	v_exp_f32_e32 v236, v236
	v_exp_f32_e32 v237, v237
	v_exp_f32_e32 v218, v218
	v_exp_f32_e32 v219, v219
	v_exp_f32_e32 v220, v220
	v_exp_f32_e32 v221, v221
	v_add_f32_e32 v234, 1.0, v234
	v_add_f32_e32 v235, 1.0, v235
	v_add_f32_e32 v236, 1.0, v236
	v_add_f32_e32 v237, 1.0, v237
	v_add_f32_e32 v218, 1.0, v218
	v_add_f32_e32 v219, 1.0, v219
	v_add_f32_e32 v220, 1.0, v220
	v_add_f32_e32 v221, 1.0, v221
	v_rcp_f32_e32 v234, v234
	v_rcp_f32_e32 v235, v235
	v_rcp_f32_e32 v236, v236
	v_rcp_f32_e32 v237, v237
	v_rcp_f32_e32 v218, v218
	v_rcp_f32_e32 v219, v219
	v_rcp_f32_e32 v220, v220
	v_rcp_f32_e32 v221, v221
	v_lshlrev_b32_e32 v226, 16, v222
	v_and_b32_e32 v222, 0xffff0000, v222
	v_fma_f32 v68, v68, v234, v226
	v_fma_f32 v69, v69, v218, v222
	v_lshlrev_b32_e32 v227, 16, v223
	v_and_b32_e32 v223, 0xffff0000, v223
	v_fma_f32 v70, v70, v235, v227
	v_fma_f32 v71, v71, v219, v223
	v_lshlrev_b32_e32 v228, 16, v224
	v_and_b32_e32 v224, 0xffff0000, v224
	v_fma_f32 v64, v64, v236, v228
	v_fma_f32 v65, v65, v220, v224
	v_lshlrev_b32_e32 v229, 16, v225
	v_and_b32_e32 v225, 0xffff0000, v225
	v_fma_f32 v66, v66, v237, v229
	v_fma_f32 v67, v67, v221, v225
	v_cvt_pk_bf16_f32 v68, v68, v69
	v_cvt_pk_bf16_f32 v69, v70, v71
	v_cvt_pk_bf16_f32 v70, v64, v65
	v_cvt_pk_bf16_f32 v71, v66, v67
	global_store_dwordx4 v153, v[68:71], s[10:11] offset:256
	global_load_dwordx4 v[218:221], v149, s[12:13] offset:256
	global_load_dwordx4 v[222:225], v149, s[10:11] offset:256
	s_waitcnt vmcnt(21)
; __device__ __forceinline__ void store8(bf16_t* dst, const float* v) { u32x4 w; w.x = pk2(v[0], v[1]); w.y = pk2(v[2], v[3]); w.z = pk2(v[4], v[5]); w.w = pk2(v[6], v[7]); *(u32x4*)dst = w; }
; __device__ __forceinline__ void load8(const bf16_t* src, float* v) { const u32x4 w = *(const u32x4*)src; v[0] = bf_lo(w.x); v[1] = bf_hi(w.x); v[2] = bf_lo(w.y); v[3] = bf_hi(w.y); v[4] = bf_lo(w.z); v[5] = bf_hi(w.z); v[6] = bf_lo(w.w); v[7] = bf_hi(w.w); }
; __device__ __forceinline__ float sigmoidf_(float v) { return __builtin_amdgcn_rcpf(1.f + __builtin_amdgcn_exp2f(-v * LOG2E)); }
;     __device__ __forceinline__ void operator()(const pg8::f32x4 (&acc)[2][2][4][2], const pg8::Unit& u, int wr, int wc, int fr, int fq) const {
;     ...
;                     } else if constexpr (KIND == EK_MIX2) {
;                         const size_t off = (size_t)row * 2048 + pn * 256 + cl; float g[8], pr[8]; load8(a.g0 + off, g); load8(a.o0 + off, pr);
; #pragma unroll
;                         for (int j = 0; j < 8; ++j) v[j] = pr[j] + v[j] * g[j];
;                         store8(a.o0 + off, v);
	v_lshlrev_b32_e32 v234, 16, v154
	v_and_b32_e32 v154, 0xffff0000, v154
	v_lshlrev_b32_e32 v235, 16, v155
	v_and_b32_e32 v155, 0xffff0000, v155
	v_lshlrev_b32_e32 v236, 16, v156
	v_and_b32_e32 v156, 0xffff0000, v156
	v_lshlrev_b32_e32 v237, 16, v157
	v_and_b32_e32 v157, 0xffff0000, v157
	v_mul_f32_e32 v234, 0xbfb8aa3b, v234
	v_mul_f32_e32 v235, 0xbfb8aa3b, v235
	v_mul_f32_e32 v236, 0xbfb8aa3b, v236
	v_mul_f32_e32 v237, 0xbfb8aa3b, v237
	v_mul_f32_e32 v154, 0xbfb8aa3b, v154
	v_mul_f32_e32 v155, 0xbfb8aa3b, v155
	v_mul_f32_e32 v156, 0xbfb8aa3b, v156
	v_mul_f32_e32 v157, 0xbfb8aa3b, v157
	v_exp_f32_e32 v234, v234
	v_exp_f32_e32 v235, v235
	v_exp_f32_e32 v236, v236
	v_exp_f32_e32 v237, v237
	v_exp_f32_e32 v154, v154
	v_exp_f32_e32 v155, v155
	v_exp_f32_e32 v156, v156
	v_exp_f32_e32 v157, v157
	v_add_f32_e32 v234, 1.0, v234
	v_add_f32_e32 v235, 1.0, v235
	v_add_f32_e32 v236, 1.0, v236
	v_add_f32_e32 v237, 1.0, v237
	v_add_f32_e32 v154, 1.0, v154
	v_add_f32_e32 v155, 1.0, v155
	v_add_f32_e32 v156, 1.0, v156
	v_add_f32_e32 v157, 1.0, v157
	v_rcp_f32_e32 v234, v234
	v_rcp_f32_e32 v235, v235
	v_rcp_f32_e32 v236, v236
	v_rcp_f32_e32 v237, v237
	v_rcp_f32_e32 v154, v154
	v_rcp_f32_e32 v155, v155
	v_rcp_f32_e32 v156, v156
	v_rcp_f32_e32 v157, v157
	v_lshlrev_b32_e32 v226, 16, v158
	v_and_b32_e32 v158, 0xffff0000, v158
	v_fma_f32 v60, v60, v234, v226
	v_fma_f32 v61, v61, v154, v158
	v_lshlrev_b32_e32 v227, 16, v159
	v_and_b32_e32 v159, 0xffff0000, v159
	v_fma_f32 v62, v62, v235, v227
	v_fma_f32 v63, v63, v155, v159
	v_lshlrev_b32_e32 v228, 16, v160
	v_and_b32_e32 v160, 0xffff0000, v160
	v_fma_f32 v56, v56, v236, v228
	v_fma_f32 v57, v57, v156, v160
	v_lshlrev_b32_e32 v229, 16, v161
	v_and_b32_e32 v161, 0xffff0000, v161
	v_fma_f32 v58, v58, v237, v229
	v_fma_f32 v59, v59, v157, v161
	v_cvt_pk_bf16_f32 v60, v60, v61
	v_cvt_pk_bf16_f32 v61, v62, v63
	v_cvt_pk_bf16_f32 v62, v56, v57
	v_cvt_pk_bf16_f32 v63, v58, v59
	v_add_u32_e32 v153, 0x80000, v148
	global_store_dwordx4 v153, v[60:63], s[10:11]
	s_waitcnt vmcnt(19)
	v_lshlrev_b32_e32 v234, 16, v162
	v_and_b32_e32 v162, 0xffff0000, v162
	v_lshlrev_b32_e32 v235, 16, v163
	v_and_b32_e32 v163, 0xffff0000, v163
	v_lshlrev_b32_e32 v236, 16, v164
	v_and_b32_e32 v164, 0xffff0000, v164
	v_lshlrev_b32_e32 v237, 16, v165
	v_and_b32_e32 v165, 0xffff0000, v165
	v_mul_f32_e32 v234, 0xbfb8aa3b, v234
	v_mul_f32_e32 v235, 0xbfb8aa3b, v235
	v_mul_f32_e32 v236, 0xbfb8aa3b, v236
	v_mul_f32_e32 v237, 0xbfb8aa3b, v237
	v_mul_f32_e32 v162, 0xbfb8aa3b, v162
	v_mul_f32_e32 v163, 0xbfb8aa3b, v163
	v_mul_f32_e32 v164, 0xbfb8aa3b, v164
	v_mul_f32_e32 v165, 0xbfb8aa3b, v165
	v_exp_f32_e32 v234, v234
	v_exp_f32_e32 v235, v235
	v_exp_f32_e32 v236, v236
	v_exp_f32_e32 v237, v237
	v_exp_f32_e32 v162, v162
	v_exp_f32_e32 v163, v163
	v_exp_f32_e32 v164, v164
	v_exp_f32_e32 v165, v165
	v_add_f32_e32 v234, 1.0, v234
	v_add_f32_e32 v235, 1.0, v235
	v_add_f32_e32 v236, 1.0, v236
	v_add_f32_e32 v237, 1.0, v237
	v_add_f32_e32 v162, 1.0, v162
	v_add_f32_e32 v163, 1.0, v163
	v_add_f32_e32 v164, 1.0, v164
	v_add_f32_e32 v165, 1.0, v165
	v_rcp_f32_e32 v234, v234
	v_rcp_f32_e32 v235, v235
	v_rcp_f32_e32 v236, v236
	v_rcp_f32_e32 v237, v237
	v_rcp_f32_e32 v162, v162
	v_rcp_f32_e32 v163, v163
	v_rcp_f32_e32 v164, v164
	v_rcp_f32_e32 v165, v165
	v_lshlrev_b32_e32 v226, 16, v168
	v_and_b32_e32 v168, 0xffff0000, v168
	v_fma_f32 v52, v52, v234, v226
	v_fma_f32 v53, v53, v162, v168
	v_lshlrev_b32_e32 v227, 16, v169
	v_and_b32_e32 v169, 0xffff0000, v169
	v_fma_f32 v54, v54, v235, v227
	v_fma_f32 v55, v55, v163, v169
	v_lshlrev_b32_e32 v228, 16, v170
	v_and_b32_e32 v170, 0xffff0000, v170
	v_fma_f32 v48, v48, v236, v228
	v_fma_f32 v49, v49, v164, v170
	v_lshlrev_b32_e32 v229, 16, v171
	v_and_b32_e32 v171, 0xffff0000, v171
	v_fma_f32 v50, v50, v237, v229
	v_fma_f32 v51, v51, v165, v171
	v_cvt_pk_bf16_f32 v52, v52, v53
	v_cvt_pk_bf16_f32 v53, v54, v55
	v_cvt_pk_bf16_f32 v54, v48, v49
	v_cvt_pk_bf16_f32 v55, v50, v51
	global_store_dwordx4 v153, v[52:55], s[10:11] offset:256
	s_waitcnt vmcnt(17)
	v_lshlrev_b32_e32 v234, 16, v172
	v_and_b32_e32 v172, 0xffff0000, v172
	v_lshlrev_b32_e32 v235, 16, v173
	v_and_b32_e32 v173, 0xffff0000, v173
	v_lshlrev_b32_e32 v236, 16, v174
	v_and_b32_e32 v174, 0xffff0000, v174
	v_lshlrev_b32_e32 v237, 16, v175
	v_and_b32_e32 v175, 0xffff0000, v175
	v_mul_f32_e32 v234, 0xbfb8aa3b, v234
	v_mul_f32_e32 v235, 0xbfb8aa3b, v235
	v_mul_f32_e32 v236, 0xbfb8aa3b, v236
	v_mul_f32_e32 v237, 0xbfb8aa3b, v237
	v_mul_f32_e32 v172, 0xbfb8aa3b, v172
	v_mul_f32_e32 v173, 0xbfb8aa3b, v173
	v_mul_f32_e32 v174, 0xbfb8aa3b, v174
	v_mul_f32_e32 v175, 0xbfb8aa3b, v175
	v_exp_f32_e32 v234, v234
	v_exp_f32_e32 v235, v235
	v_exp_f32_e32 v236, v236
	v_exp_f32_e32 v237, v237
	v_exp_f32_e32 v172, v172
	v_exp_f32_e32 v173, v173
	v_exp_f32_e32 v174, v174
	v_exp_f32_e32 v175, v175
	v_add_f32_e32 v234, 1.0, v234
	v_add_f32_e32 v235, 1.0, v235
	v_add_f32_e32 v236, 1.0, v236
	v_add_f32_e32 v237, 1.0, v237
	v_add_f32_e32 v172, 1.0, v172
	v_add_f32_e32 v173, 1.0, v173
	v_add_f32_e32 v174, 1.0, v174
	v_add_f32_e32 v175, 1.0, v175
	v_rcp_f32_e32 v234, v234
	v_rcp_f32_e32 v235, v235
	v_rcp_f32_e32 v236, v236
	v_rcp_f32_e32 v237, v237
	v_rcp_f32_e32 v172, v172
	v_rcp_f32_e32 v173, v173
	v_rcp_f32_e32 v174, v174
	v_rcp_f32_e32 v175, v175
	v_lshlrev_b32_e32 v226, 16, v182
	v_and_b32_e32 v182, 0xffff0000, v182
	v_fma_f32 v44, v44, v234, v226
	v_fma_f32 v45, v45, v172, v182
	v_lshlrev_b32_e32 v227, 16, v183
	v_and_b32_e32 v183, 0xffff0000, v183
	v_fma_f32 v46, v46, v235, v227
	v_fma_f32 v47, v47, v173, v183
	v_lshlrev_b32_e32 v228, 16, v184
	v_and_b32_e32 v184, 0xffff0000, v184
	v_fma_f32 v40, v40, v236, v228
	v_fma_f32 v41, v41, v174, v184
	v_lshlrev_b32_e32 v229, 16, v185
	v_and_b32_e32 v185, 0xffff0000, v185
	v_fma_f32 v42, v42, v237, v229
	v_fma_f32 v43, v43, v175, v185
	v_cvt_pk_bf16_f32 v44, v44, v45
	v_cvt_pk_bf16_f32 v45, v46, v47
	v_cvt_pk_bf16_f32 v46, v40, v41
	v_cvt_pk_bf16_f32 v47, v42, v43
	v_add_u32_e32 v153, 0x90000, v148
	global_store_dwordx4 v153, v[44:47], s[10:11]
	s_waitcnt vmcnt(15)
; __device__ __forceinline__ void store8(bf16_t* dst, const float* v) { u32x4 w; w.x = pk2(v[0], v[1]); w.y = pk2(v[2], v[3]); w.z = pk2(v[4], v[5]); w.w = pk2(v[6], v[7]); *(u32x4*)dst = w; }
; __device__ __forceinline__ void load8(const bf16_t* src, float* v) { const u32x4 w = *(const u32x4*)src; v[0] = bf_lo(w.x); v[1] = bf_hi(w.x); v[2] = bf_lo(w.y); v[3] = bf_hi(w.y); v[4] = bf_lo(w.z); v[5] = bf_hi(w.z); v[6] = bf_lo(w.w); v[7] = bf_hi(w.w); }
; __device__ __forceinline__ float sigmoidf_(float v) { return __builtin_amdgcn_rcpf(1.f + __builtin_amdgcn_exp2f(-v * LOG2E)); }
;     __device__ __forceinline__ void operator()(const pg8::f32x4 (&acc)[2][2][4][2], const pg8::Unit& u, int wr, int wc, int fr, int fq) const {
;     ...
;                     } else if constexpr (KIND == EK_MIX2) {
;                         const size_t off = (size_t)row * 2048 + pn * 256 + cl; float g[8], pr[8]; load8(a.g0 + off, g); load8(a.o0 + off, pr);
; #pragma unroll
;                         for (int j = 0; j < 8; ++j) v[j] = pr[j] + v[j] * g[j];
;                         store8(a.o0 + off, v);
	v_lshlrev_b32_e32 v234, 16, v186
	v_and_b32_e32 v186, 0xffff0000, v186
	v_lshlrev_b32_e32 v235, 16, v187
	v_and_b32_e32 v187, 0xffff0000, v187
	v_lshlrev_b32_e32 v236, 16, v188
	v_and_b32_e32 v188, 0xffff0000, v188
	v_lshlrev_b32_e32 v237, 16, v189
	v_and_b32_e32 v189, 0xffff0000, v189
	v_mul_f32_e32 v234, 0xbfb8aa3b, v234
	v_mul_f32_e32 v235, 0xbfb8aa3b, v235
	v_mul_f32_e32 v236, 0xbfb8aa3b, v236
	v_mul_f32_e32 v237, 0xbfb8aa3b, v237
	v_mul_f32_e32 v186, 0xbfb8aa3b, v186
	v_mul_f32_e32 v187, 0xbfb8aa3b, v187
	v_mul_f32_e32 v188, 0xbfb8aa3b, v188
	v_mul_f32_e32 v189, 0xbfb8aa3b, v189
	v_exp_f32_e32 v234, v234
	v_exp_f32_e32 v235, v235
	v_exp_f32_e32 v236, v236
	v_exp_f32_e32 v237, v237
	v_exp_f32_e32 v186, v186
	v_exp_f32_e32 v187, v187
	v_exp_f32_e32 v188, v188
	v_exp_f32_e32 v189, v189
	v_add_f32_e32 v234, 1.0, v234
	v_add_f32_e32 v235, 1.0, v235
	v_add_f32_e32 v236, 1.0, v236
	v_add_f32_e32 v237, 1.0, v237
	v_add_f32_e32 v186, 1.0, v186
	v_add_f32_e32 v187, 1.0, v187
	v_add_f32_e32 v188, 1.0, v188
	v_add_f32_e32 v189, 1.0, v189
	v_rcp_f32_e32 v234, v234
	v_rcp_f32_e32 v235, v235
	v_rcp_f32_e32 v236, v236
	v_rcp_f32_e32 v237, v237
	v_rcp_f32_e32 v186, v186
	v_rcp_f32_e32 v187, v187
	v_rcp_f32_e32 v188, v188
	v_rcp_f32_e32 v189, v189
	v_lshlrev_b32_e32 v226, 16, v190
	v_and_b32_e32 v190, 0xffff0000, v190
	v_fma_f32 v36, v36, v234, v226
	v_fma_f32 v37, v37, v186, v190
	v_lshlrev_b32_e32 v227, 16, v191
	v_and_b32_e32 v191, 0xffff0000, v191
	v_fma_f32 v38, v38, v235, v227
	v_fma_f32 v39, v39, v187, v191
	v_lshlrev_b32_e32 v228, 16, v192
	v_and_b32_e32 v192, 0xffff0000, v192
	v_fma_f32 v32, v32, v236, v228
	v_fma_f32 v33, v33, v188, v192
	v_lshlrev_b32_e32 v229, 16, v193
	v_and_b32_e32 v193, 0xffff0000, v193
	v_fma_f32 v34, v34, v237, v229
	v_fma_f32 v35, v35, v189, v193
	v_cvt_pk_bf16_f32 v36, v36, v37
	v_cvt_pk_bf16_f32 v37, v38, v39
	v_cvt_pk_bf16_f32 v38, v32, v33
	v_cvt_pk_bf16_f32 v39, v34, v35
	global_store_dwordx4 v153, v[36:39], s[10:11] offset:256
	s_waitcnt vmcnt(13)
	v_lshlrev_b32_e32 v234, 16, v194
	v_and_b32_e32 v194, 0xffff0000, v194
	v_lshlrev_b32_e32 v235, 16, v195
	v_and_b32_e32 v195, 0xffff0000, v195
	v_lshlrev_b32_e32 v236, 16, v196
	v_and_b32_e32 v196, 0xffff0000, v196
	v_lshlrev_b32_e32 v237, 16, v197
	v_and_b32_e32 v197, 0xffff0000, v197
	v_mul_f32_e32 v234, 0xbfb8aa3b, v234
	v_mul_f32_e32 v235, 0xbfb8aa3b, v235
	v_mul_f32_e32 v236, 0xbfb8aa3b, v236
	v_mul_f32_e32 v237, 0xbfb8aa3b, v237
	v_mul_f32_e32 v194, 0xbfb8aa3b, v194
	v_mul_f32_e32 v195, 0xbfb8aa3b, v195
	v_mul_f32_e32 v196, 0xbfb8aa3b, v196
	v_mul_f32_e32 v197, 0xbfb8aa3b, v197
	v_exp_f32_e32 v234, v234
	v_exp_f32_e32 v235, v235
	v_exp_f32_e32 v236, v236
	v_exp_f32_e32 v237, v237
	v_exp_f32_e32 v194, v194
	v_exp_f32_e32 v195, v195
	v_exp_f32_e32 v196, v196
	v_exp_f32_e32 v197, v197
	v_add_f32_e32 v234, 1.0, v234
	v_add_f32_e32 v235, 1.0, v235
	v_add_f32_e32 v236, 1.0, v236
	v_add_f32_e32 v237, 1.0, v237
	v_add_f32_e32 v194, 1.0, v194
	v_add_f32_e32 v195, 1.0, v195
	v_add_f32_e32 v196, 1.0, v196
	v_add_f32_e32 v197, 1.0, v197
	v_rcp_f32_e32 v234, v234
	v_rcp_f32_e32 v235, v235
	v_rcp_f32_e32 v236, v236
	v_rcp_f32_e32 v237, v237
	v_rcp_f32_e32 v194, v194
	v_rcp_f32_e32 v195, v195
	v_rcp_f32_e32 v196, v196
	v_rcp_f32_e32 v197, v197
	v_lshlrev_b32_e32 v226, 16, v198
	v_and_b32_e32 v198, 0xffff0000, v198
	v_fma_f32 v28, v28, v234, v226
	v_fma_f32 v29, v29, v194, v198
	v_lshlrev_b32_e32 v227, 16, v199
	v_and_b32_e32 v199, 0xffff0000, v199
	v_fma_f32 v30, v30, v235, v227
	v_fma_f32 v31, v31, v195, v199
	v_lshlrev_b32_e32 v228, 16, v200
	v_and_b32_e32 v200, 0xffff0000, v200
	v_fma_f32 v24, v24, v236, v228
	v_fma_f32 v25, v25, v196, v200
	v_lshlrev_b32_e32 v229, 16, v201
	v_and_b32_e32 v201, 0xffff0000, v201
	v_fma_f32 v26, v26, v237, v229
	v_fma_f32 v27, v27, v197, v201
	v_cvt_pk_bf16_f32 v28, v28, v29
	v_cvt_pk_bf16_f32 v29, v30, v31
	v_cvt_pk_bf16_f32 v30, v24, v25
	v_cvt_pk_bf16_f32 v31, v26, v27
	v_add_u32_e32 v153, 0xa0000, v148
	global_store_dwordx4 v153, v[28:31], s[10:11]
	s_waitcnt vmcnt(11)
	v_lshlrev_b32_e32 v234, 16, v202
	v_and_b32_e32 v202, 0xffff0000, v202
	v_lshlrev_b32_e32 v235, 16, v203
	v_and_b32_e32 v203, 0xffff0000, v203
	v_lshlrev_b32_e32 v236, 16, v204
	v_and_b32_e32 v204, 0xffff0000, v204
	v_lshlrev_b32_e32 v237, 16, v205
	v_and_b32_e32 v205, 0xffff0000, v205
	v_mul_f32_e32 v234, 0xbfb8aa3b, v234
	v_mul_f32_e32 v235, 0xbfb8aa3b, v235
	v_mul_f32_e32 v236, 0xbfb8aa3b, v236
	v_mul_f32_e32 v237, 0xbfb8aa3b, v237
	v_mul_f32_e32 v202, 0xbfb8aa3b, v202
	v_mul_f32_e32 v203, 0xbfb8aa3b, v203
	v_mul_f32_e32 v204, 0xbfb8aa3b, v204
	v_mul_f32_e32 v205, 0xbfb8aa3b, v205
	v_exp_f32_e32 v234, v234
	v_exp_f32_e32 v235, v235
	v_exp_f32_e32 v236, v236
	v_exp_f32_e32 v237, v237
	v_exp_f32_e32 v202, v202
	v_exp_f32_e32 v203, v203
	v_exp_f32_e32 v204, v204
	v_exp_f32_e32 v205, v205
	v_add_f32_e32 v234, 1.0, v234
	v_add_f32_e32 v235, 1.0, v235
	v_add_f32_e32 v236, 1.0, v236
	v_add_f32_e32 v237, 1.0, v237
	v_add_f32_e32 v202, 1.0, v202
	v_add_f32_e32 v203, 1.0, v203
	v_add_f32_e32 v204, 1.0, v204
	v_add_f32_e32 v205, 1.0, v205
	v_rcp_f32_e32 v234, v234
	v_rcp_f32_e32 v235, v235
	v_rcp_f32_e32 v236, v236
	v_rcp_f32_e32 v237, v237
	v_rcp_f32_e32 v202, v202
	v_rcp_f32_e32 v203, v203
	v_rcp_f32_e32 v204, v204
	v_rcp_f32_e32 v205, v205
	v_lshlrev_b32_e32 v226, 16, v206
	v_and_b32_e32 v206, 0xffff0000, v206
	v_fma_f32 v20, v20, v234, v226
	v_fma_f32 v21, v21, v202, v206
	v_lshlrev_b32_e32 v227, 16, v207
	v_and_b32_e32 v207, 0xffff0000, v207
	v_fma_f32 v22, v22, v235, v227
	v_fma_f32 v23, v23, v203, v207
	v_lshlrev_b32_e32 v228, 16, v208
	v_and_b32_e32 v208, 0xffff0000, v208
	v_fma_f32 v16, v16, v236, v228
	v_fma_f32 v17, v17, v204, v208
	v_lshlrev_b32_e32 v229, 16, v209
	v_and_b32_e32 v209, 0xffff0000, v209
	v_fma_f32 v18, v18, v237, v229
	v_fma_f32 v19, v19, v205, v209
	v_cvt_pk_bf16_f32 v20, v20, v21
	v_cvt_pk_bf16_f32 v21, v22, v23
	v_cvt_pk_bf16_f32 v22, v16, v17
	v_cvt_pk_bf16_f32 v23, v18, v19
	global_store_dwordx4 v153, v[20:23], s[10:11] offset:256
	s_waitcnt vmcnt(9)
; #define PG8_BAR __builtin_amdgcn_s_barrier()
; __device__ __forceinline__ void store8(bf16_t* dst, const float* v) { u32x4 w; w.x = pk2(v[0], v[1]); w.y = pk2(v[2], v[3]); w.z = pk2(v[4], v[5]); w.w = pk2(v[6], v[7]); *(u32x4*)dst = w; }
; __device__ __forceinline__ void load8(const bf16_t* src, float* v) { const u32x4 w = *(const u32x4*)src; v[0] = bf_lo(w.x); v[1] = bf_hi(w.x); v[2] = bf_lo(w.y); v[3] = bf_hi(w.y); v[4] = bf_lo(w.z); v[5] = bf_hi(w.z); v[6] = bf_lo(w.w); v[7] = bf_hi(w.w); }
; template <class Epi, class Sched, bool ALIGN_EPI = false, bool SP2 = false>
; __device__ __forceinline__ void gemm_phase(PG8_LAS unsigned char* lds, const Gemm g, const Sched& S, const Epi& E) {
;     ...
;         if constexpr (ALIGN_EPI) { if (wr == 1) PG8_BAR; }
;     __device__ __forceinline__ void operator()(const pg8::f32x4 (&acc)[2][2][4][2], const pg8::Unit& u, int wr, int wc, int fr, int fq) const {
;     ...
;                     } else if constexpr (KIND == EK_MIX2) {
;                         const size_t off = (size_t)row * 2048 + pn * 256 + cl; float g[8], pr[8]; load8(a.g0 + off, g); load8(a.o0 + off, pr);
; #pragma unroll
;                         for (int j = 0; j < 8; ++j) v[j] = pr[j] + v[j] * g[j];
;                         store8(a.o0 + off, v);
	v_lshlrev_b32_e32 v234, 16, v210
	v_and_b32_e32 v210, 0xffff0000, v210
	v_lshlrev_b32_e32 v235, 16, v211
	v_and_b32_e32 v211, 0xffff0000, v211
	v_lshlrev_b32_e32 v236, 16, v212
	v_and_b32_e32 v212, 0xffff0000, v212
	v_lshlrev_b32_e32 v237, 16, v213
	v_and_b32_e32 v213, 0xffff0000, v213
	v_mul_f32_e32 v234, 0xbfb8aa3b, v234
	v_mul_f32_e32 v235, 0xbfb8aa3b, v235
	v_mul_f32_e32 v236, 0xbfb8aa3b, v236
	v_mul_f32_e32 v237, 0xbfb8aa3b, v237
	v_mul_f32_e32 v210, 0xbfb8aa3b, v210
	v_mul_f32_e32 v211, 0xbfb8aa3b, v211
	v_mul_f32_e32 v212, 0xbfb8aa3b, v212
	v_mul_f32_e32 v213, 0xbfb8aa3b, v213
	v_exp_f32_e32 v234, v234
	v_exp_f32_e32 v235, v235
	v_exp_f32_e32 v236, v236
	v_exp_f32_e32 v237, v237
	v_exp_f32_e32 v210, v210
	v_exp_f32_e32 v211, v211
	v_exp_f32_e32 v212, v212
	v_exp_f32_e32 v213, v213
	v_add_f32_e32 v234, 1.0, v234
	v_add_f32_e32 v235, 1.0, v235
	v_add_f32_e32 v236, 1.0, v236
	v_add_f32_e32 v237, 1.0, v237
	v_add_f32_e32 v210, 1.0, v210
	v_add_f32_e32 v211, 1.0, v211
	v_add_f32_e32 v212, 1.0, v212
	v_add_f32_e32 v213, 1.0, v213
	v_rcp_f32_e32 v234, v234
	v_rcp_f32_e32 v235, v235
	v_rcp_f32_e32 v236, v236
	v_rcp_f32_e32 v237, v237
	v_rcp_f32_e32 v210, v210
	v_rcp_f32_e32 v211, v211
	v_rcp_f32_e32 v212, v212
	v_rcp_f32_e32 v213, v213
	v_lshlrev_b32_e32 v226, 16, v214
	v_and_b32_e32 v214, 0xffff0000, v214
	v_fma_f32 v12, v12, v234, v226
	v_fma_f32 v13, v13, v210, v214
	v_lshlrev_b32_e32 v227, 16, v215
	v_and_b32_e32 v215, 0xffff0000, v215
	v_fma_f32 v14, v14, v235, v227
	v_fma_f32 v15, v15, v211, v215
	v_lshlrev_b32_e32 v228, 16, v216
	v_and_b32_e32 v216, 0xffff0000, v216
	v_fma_f32 v8, v8, v236, v228
	v_fma_f32 v9, v9, v212, v216
	v_lshlrev_b32_e32 v229, 16, v217
	v_and_b32_e32 v217, 0xffff0000, v217
	v_fma_f32 v10, v10, v237, v229
	v_fma_f32 v11, v11, v213, v217
	v_cvt_pk_bf16_f32 v12, v12, v13
	v_cvt_pk_bf16_f32 v13, v14, v15
	v_cvt_pk_bf16_f32 v14, v8, v9
	v_cvt_pk_bf16_f32 v15, v10, v11
	v_add_u32_e32 v153, 0xb0000, v148
	global_store_dwordx4 v153, v[12:15], s[10:11]
	s_waitcnt vmcnt(7)
	v_lshlrev_b32_e32 v234, 16, v218
	v_and_b32_e32 v218, 0xffff0000, v218
	v_lshlrev_b32_e32 v235, 16, v219
	v_and_b32_e32 v219, 0xffff0000, v219
	v_lshlrev_b32_e32 v236, 16, v220
	v_and_b32_e32 v220, 0xffff0000, v220
	v_lshlrev_b32_e32 v237, 16, v221
	v_and_b32_e32 v221, 0xffff0000, v221
	v_mul_f32_e32 v234, 0xbfb8aa3b, v234
	v_mul_f32_e32 v235, 0xbfb8aa3b, v235
	v_mul_f32_e32 v236, 0xbfb8aa3b, v236
	v_mul_f32_e32 v237, 0xbfb8aa3b, v237
	v_mul_f32_e32 v218, 0xbfb8aa3b, v218
	v_mul_f32_e32 v219, 0xbfb8aa3b, v219
	v_mul_f32_e32 v220, 0xbfb8aa3b, v220
	v_mul_f32_e32 v221, 0xbfb8aa3b, v221
	v_exp_f32_e32 v234, v234
	v_exp_f32_e32 v235, v235
	v_exp_f32_e32 v236, v236
	v_exp_f32_e32 v237, v237
	v_exp_f32_e32 v218, v218
	v_exp_f32_e32 v219, v219
	v_exp_f32_e32 v220, v220
	v_exp_f32_e32 v221, v221
	v_add_f32_e32 v234, 1.0, v234
	v_add_f32_e32 v235, 1.0, v235
	v_add_f32_e32 v236, 1.0, v236
	v_add_f32_e32 v237, 1.0, v237
	v_add_f32_e32 v218, 1.0, v218
	v_add_f32_e32 v219, 1.0, v219
	v_add_f32_e32 v220, 1.0, v220
	v_add_f32_e32 v221, 1.0, v221
	v_rcp_f32_e32 v234, v234
	v_rcp_f32_e32 v235, v235
	v_rcp_f32_e32 v236, v236
	v_rcp_f32_e32 v237, v237
	v_rcp_f32_e32 v218, v218
	v_rcp_f32_e32 v219, v219
	v_rcp_f32_e32 v220, v220
	v_rcp_f32_e32 v221, v221
	v_lshlrev_b32_e32 v226, 16, v222
	v_and_b32_e32 v222, 0xffff0000, v222
	v_fma_f32 v4, v4, v234, v226
	v_fma_f32 v5, v5, v218, v222
	v_lshlrev_b32_e32 v227, 16, v223
	v_and_b32_e32 v223, 0xffff0000, v223
	v_fma_f32 v6, v6, v235, v227
	v_fma_f32 v7, v7, v219, v223
	v_lshlrev_b32_e32 v228, 16, v224
	v_and_b32_e32 v224, 0xffff0000, v224
	v_fma_f32 v0, v0, v236, v228
	v_fma_f32 v1, v1, v220, v224
	v_lshlrev_b32_e32 v229, 16, v225
	v_and_b32_e32 v225, 0xffff0000, v225
	v_fma_f32 v2, v2, v237, v229
	v_fma_f32 v3, v3, v221, v225
	v_cvt_pk_bf16_f32 v4, v4, v5
	v_cvt_pk_bf16_f32 v5, v6, v7
	v_cvt_pk_bf16_f32 v6, v0, v1
	v_cvt_pk_bf16_f32 v7, v2, v3
	global_store_dwordx4 v153, v[4:7], s[10:11] offset:256
	s_andn2_b64 vcc, exec, s[6:7]
	s_mov_b64 s[6:7], -1
	s_cbranch_vccnz .LBB0_1065
	s_andn2_b64 vcc, exec, s[8:9]
	s_cbranch_vccnz .LBB0_1064
	s_barrier
	s_branch .LBB0_1064
